# write-through (sc1) stores for the SwiGLU epilogue activation stream only (largest cross-XCD published buffer), everything else plain
# speedup vs baseline: 1.0058x; 1.0036x over previous
; __device__ __forceinline__ unsigned cvtpk(float lo, float hi) { f32x2_t v = {lo, hi}; bf16x2_t b = __builtin_convertvector(v, bf16x2_t); return __builtin_bit_cast(unsigned, b); }
; __device__ __forceinline__ float ss_rs(u64 v) { return 1.f / sqrtf((float)v * (SSFI / 1024.f) + 1e-6f); }
;     __device__ __forceinline__ void operator()(const Acc& acc, const Unit& u, int wr, int wc, int fr, int fq) const {
;         const int row0 = u.pm * BM + wr * 64 + fr, col0 = u.pn * 128 + wc * 32 + 8 * fq;
;         u64 sv[2][4];
; #pragma unroll
;         for (int ai = 0; ai < 2; ++ai)
; #pragma unroll
;             for (int m = 0; m < 4; ++m) sv[ai][m] = SS[row0 + ai * HALF + m * 16];
; #pragma unroll
;         for (int ai = 0; ai < 2; ++ai)
; #pragma unroll
;             for (int m = 0; m < 4; ++m) {
;                 const int row = row0 + ai * HALF + m * 16; const float rs = ss_rs(sv[ai][m]);
;                 unsigned w[4];
; #pragma unroll
;                 for (int n = 0; n < 2; ++n) {
;                     const f32x4 gv = acc[ai][0][m][n] * rs, uv = acc[ai][1][m][n] * rs; float h[4];
; #pragma unroll
;                     for (int e = 0; e < 4; ++e) { const float gg = gv[e]; h[e] = gg * __builtin_amdgcn_rcpf(1.f + __builtin_amdgcn_exp2f(-1.4426950408889634f * gg)) * uv[e]; }
;                     w[2 * n] = cvtpk(h[0], h[1]); w[2 * n + 1] = cvtpk(h[2], h[3]);
;                 }
;                 *(u32x4*)(O + (size_t)row * DFF + col0) = (u32x4){w[0], w[1], w[2], w[3]};
;             }
.LBB0_84:
	v_lshl_add_u32 v152, s0, 8, v156
	v_ashrrev_i32_e32 v153, 31, v152
	v_lshl_add_u64 v[138:139], v[152:153], 3, s[44:45]
	global_load_dwordx2 v[168:169], v[138:139], off
	global_load_dwordx2 v[150:151], v[138:139], off offset:128
	global_load_dwordx2 v[148:149], v[138:139], off offset:256
	global_load_dwordx2 v[146:147], v[138:139], off offset:384
	v_lshl_or_b32 v154, s1, 7, v158
	v_ashrrev_i32_e32 v155, 31, v154
	global_load_dwordx2 v[144:145], v[138:139], off offset:1024
	global_load_dwordx2 v[142:143], v[138:139], off offset:1152
	global_load_dwordx2 v[140:141], v[138:139], off offset:1280
	v_or_b32_e32 v167, 16, v152
	global_load_dwordx2 v[138:139], v[138:139], off offset:1408
	v_or_b32_e32 v166, 32, v152
	v_or_b32_e32 v165, 48, v152
	v_add_u32_e32 v164, 0x80, v152
	v_add_u32_e32 v163, 0x90, v152
	v_add_u32_e32 v162, 0xa0, v152
	v_add_u32_e32 v153, 0xb0, v152
	s_waitcnt vmcnt(0)
	v_ffbh_u32_e32 v170, v169
	v_min_u32_e32 v170, 32, v170
	v_lshlrev_b64 v[168:169], v170, v[168:169]
	v_min_u32_e32 v168, 1, v168
	v_or_b32_e32 v168, v169, v168
	v_cvt_f32_u32_e32 v168, v168
	v_sub_u32_e32 v169, 32, v170
	v_ldexp_f32 v168, v168, v169
	v_fmamk_f32 v168, v168, 0x2e800000, v226
	v_cmp_gt_f32_e32 vcc, s31, v168
	v_mul_f32_e32 v169, 0x4f800000, v168
	s_nop 0
	v_cndmask_b32_e32 v168, v168, v169, vcc
	v_sqrt_f32_e32 v169, v168
	s_nop 0
	v_add_u32_e32 v170, -1, v169
	v_fma_f32 v171, -v170, v169, v168
	v_cmp_ge_f32_e64 s[42:43], 0, v171
	v_add_u32_e32 v171, 1, v169
	s_nop 0
	v_cndmask_b32_e64 v170, v169, v170, s[42:43]
	v_fma_f32 v169, -v171, v169, v168
	v_cmp_lt_f32_e64 s[42:43], 0, v169
	s_nop 1
	v_cndmask_b32_e64 v169, v170, v171, s[42:43]
	v_mul_f32_e32 v170, 0x37800000, v169
	v_cndmask_b32_e32 v169, v169, v170, vcc
	v_cmp_class_f32_e32 vcc, v168, v227
	s_nop 1
	v_cndmask_b32_e32 v168, v169, v168, vcc
	v_div_scale_f32 v169, s[0:1], v168, v168, 1.0
	v_rcp_f32_e32 v170, v169
	s_nop 0
	v_fma_f32 v171, -v169, v170, 1.0
	v_fmac_f32_e32 v170, v171, v170
	v_div_scale_f32 v171, vcc, 1.0, v168, 1.0
	v_mul_f32_e32 v172, v171, v170
	v_fma_f32 v173, -v169, v172, v171
	v_fmac_f32_e32 v172, v173, v170
	v_fma_f32 v169, -v169, v172, v171
	v_div_fmas_f32 v169, v169, v170, v172
	v_div_fixup_f32 v168, v169, v168, 1.0
	v_pk_mul_f32 v[124:125], v[124:125], v[168:169] op_sel_hi:[1,0]
	s_nop 0
	v_mul_f32_e32 v169, 0xbfb8aa3b, v124
	v_exp_f32_e32 v169, v169
	s_nop 0
	v_add_f32_e32 v169, 1.0, v169
	v_rcp_f32_e32 v170, v169
	v_mul_f32_e32 v169, 0xbfb8aa3b, v125
	v_exp_f32_e32 v169, v169
	s_nop 0
	v_add_f32_e32 v169, 1.0, v169
	v_rcp_f32_e32 v171, v169
	v_pk_mul_f32 v[116:117], v[116:117], v[168:169] op_sel_hi:[1,0]
	v_pk_mul_f32 v[118:119], v[118:119], v[168:169] op_sel_hi:[1,0]
	v_pk_mul_f32 v[112:113], v[112:113], v[168:169] op_sel_hi:[1,0]
	v_pk_mul_f32 v[124:125], v[124:125], v[170:171]
	v_pk_mul_f32 v[114:115], v[114:115], v[168:169] op_sel_hi:[1,0]
	v_pk_mul_f32 v[116:117], v[116:117], v[124:125]
	v_pk_mul_f32 v[124:125], v[126:127], v[168:169] op_sel_hi:[1,0]
	v_cvt_pk_bf16_f32 v116, v116, v117
	v_mul_f32_e32 v126, 0xbfb8aa3b, v124
	v_mul_f32_e32 v127, 0xbfb8aa3b, v125
	v_exp_f32_e32 v126, v126
	v_exp_f32_e32 v127, v127
	v_add_f32_e32 v126, 1.0, v126
	v_add_f32_e32 v127, 1.0, v127
	v_rcp_f32_e32 v126, v126
	v_rcp_f32_e32 v127, v127
	s_nop 0
	v_pk_mul_f32 v[124:125], v[124:125], v[126:127]
	s_nop 0
	v_pk_mul_f32 v[118:119], v[118:119], v[124:125]
	s_nop 0
	v_cvt_pk_bf16_f32 v117, v118, v119
	v_pk_mul_f32 v[118:119], v[120:121], v[168:169] op_sel_hi:[1,0]
	s_nop 0
	v_mul_f32_e32 v120, 0xbfb8aa3b, v118
	v_mul_f32_e32 v121, 0xbfb8aa3b, v119
	v_exp_f32_e32 v120, v120
	v_exp_f32_e32 v121, v121
	v_add_f32_e32 v120, 1.0, v120
	v_add_f32_e32 v121, 1.0, v121
	v_rcp_f32_e32 v120, v120
	v_rcp_f32_e32 v121, v121
	s_nop 0
	v_pk_mul_f32 v[118:119], v[118:119], v[120:121]
	s_nop 0
	v_pk_mul_f32 v[112:113], v[112:113], v[118:119]
	v_pk_mul_f32 v[118:119], v[122:123], v[168:169] op_sel_hi:[1,0]
	s_nop 0
	v_mul_f32_e32 v120, 0xbfb8aa3b, v118
	v_mul_f32_e32 v121, 0xbfb8aa3b, v119
	v_exp_f32_e32 v120, v120
	v_exp_f32_e32 v121, v121
	v_add_f32_e32 v120, 1.0, v120
	v_add_f32_e32 v121, 1.0, v121
	v_rcp_f32_e32 v120, v120
	v_rcp_f32_e32 v121, v121
	s_nop 0
	v_pk_mul_f32 v[118:119], v[118:119], v[120:121]
	s_nop 0
	v_pk_mul_f32 v[114:115], v[114:115], v[118:119]
	v_cvt_pk_bf16_f32 v118, v112, v113
	v_mov_b64_e32 v[112:113], s[36:37]
	v_cvt_pk_bf16_f32 v119, v114, v115
	v_mad_i64_i32 v[120:121], s[0:1], v152, s82, v[112:113]
	v_lshlrev_b64 v[114:115], 1, v[154:155]
	v_lshl_add_u64 v[120:121], v[120:121], 0, v[114:115]
	global_store_dwordx4 v[120:121], v[116:119], off sc1
	s_nop 1
	v_ffbh_u32_e32 v116, v151
	v_min_u32_e32 v118, 32, v116
	v_lshlrev_b64 v[116:117], v118, v[150:151]
	v_min_u32_e32 v116, 1, v116
	v_or_b32_e32 v116, v117, v116
	v_cvt_f32_u32_e32 v116, v116
	v_sub_u32_e32 v117, 32, v118
	v_ldexp_f32 v116, v116, v117
	v_fmamk_f32 v116, v116, 0x2e800000, v226
	v_cmp_gt_f32_e32 vcc, s31, v116
	v_mul_f32_e32 v117, 0x4f800000, v116
	s_nop 0
	v_cndmask_b32_e32 v116, v116, v117, vcc
	v_sqrt_f32_e32 v117, v116
	s_nop 0
	v_add_u32_e32 v118, -1, v117
	v_fma_f32 v119, -v118, v117, v116
	v_cmp_ge_f32_e64 s[42:43], 0, v119
	v_add_u32_e32 v119, 1, v117
	s_nop 0
	v_cndmask_b32_e64 v118, v117, v118, s[42:43]
	v_fma_f32 v117, -v119, v117, v116
	v_cmp_lt_f32_e64 s[42:43], 0, v117
	s_nop 1
	v_cndmask_b32_e64 v117, v118, v119, s[42:43]
	v_mul_f32_e32 v118, 0x37800000, v117
	v_cndmask_b32_e32 v117, v117, v118, vcc
	v_cmp_class_f32_e32 vcc, v116, v227
	s_nop 1
	v_cndmask_b32_e32 v116, v117, v116, vcc
	v_div_scale_f32 v117, s[0:1], v116, v116, 1.0
	v_rcp_f32_e32 v118, v117
	s_nop 0
; __device__ __forceinline__ unsigned cvtpk(float lo, float hi) { f32x2_t v = {lo, hi}; bf16x2_t b = __builtin_convertvector(v, bf16x2_t); return __builtin_bit_cast(unsigned, b); }
; __device__ __forceinline__ float ss_rs(u64 v) { return 1.f / sqrtf((float)v * (SSFI / 1024.f) + 1e-6f); }
;     __device__ __forceinline__ void operator()(const Acc& acc, const Unit& u, int wr, int wc, int fr, int fq) const {
;     ...
;             for (int m = 0; m < 4; ++m) sv[ai][m] = SS[row0 + ai * HALF + m * 16];
; #pragma unroll
;         for (int ai = 0; ai < 2; ++ai)
; #pragma unroll
;             for (int m = 0; m < 4; ++m) {
;                 const int row = row0 + ai * HALF + m * 16; const float rs = ss_rs(sv[ai][m]);
;                 unsigned w[4];
; #pragma unroll
;                 for (int n = 0; n < 2; ++n) {
;                     const f32x4 gv = acc[ai][0][m][n] * rs, uv = acc[ai][1][m][n] * rs; float h[4];
; #pragma unroll
;                     for (int e = 0; e < 4; ++e) { const float gg = gv[e]; h[e] = gg * __builtin_amdgcn_rcpf(1.f + __builtin_amdgcn_exp2f(-1.4426950408889634f * gg)) * uv[e]; }
;                     w[2 * n] = cvtpk(h[0], h[1]); w[2 * n + 1] = cvtpk(h[2], h[3]);
;                 }
;                 *(u32x4*)(O + (size_t)row * DFF + col0) = (u32x4){w[0], w[1], w[2], w[3]};
	v_fma_f32 v119, -v117, v118, 1.0
	v_fmac_f32_e32 v118, v119, v118
	v_div_scale_f32 v119, vcc, 1.0, v116, 1.0
	v_mul_f32_e32 v120, v119, v118
	v_fma_f32 v121, -v117, v120, v119
	v_fmac_f32_e32 v120, v121, v118
	v_fma_f32 v117, -v117, v120, v119
	v_div_fmas_f32 v117, v117, v118, v120
	v_div_fixup_f32 v116, v117, v116, 1.0
	v_pk_mul_f32 v[108:109], v[108:109], v[116:117] op_sel_hi:[1,0]
	s_nop 0
	v_mul_f32_e32 v117, 0xbfb8aa3b, v108
	v_exp_f32_e32 v117, v117
	s_nop 0
	v_add_f32_e32 v117, 1.0, v117
	v_rcp_f32_e32 v118, v117
	v_mul_f32_e32 v117, 0xbfb8aa3b, v109
	v_exp_f32_e32 v117, v117
	s_nop 0
	v_add_f32_e32 v117, 1.0, v117
	v_rcp_f32_e32 v119, v117
	v_pk_mul_f32 v[104:105], v[104:105], v[116:117] op_sel_hi:[1,0]
	v_pk_mul_f32 v[106:107], v[106:107], v[116:117] op_sel_hi:[1,0]
	v_pk_mul_f32 v[100:101], v[100:101], v[116:117] op_sel_hi:[1,0]
	v_pk_mul_f32 v[108:109], v[108:109], v[118:119]
	v_pk_mul_f32 v[96:97], v[96:97], v[116:117] op_sel_hi:[1,0]
	v_pk_mul_f32 v[104:105], v[104:105], v[108:109]
	v_pk_mul_f32 v[108:109], v[110:111], v[116:117] op_sel_hi:[1,0]
	v_cvt_pk_bf16_f32 v104, v104, v105
	v_mul_f32_e32 v110, 0xbfb8aa3b, v108
	v_mul_f32_e32 v111, 0xbfb8aa3b, v109
	v_exp_f32_e32 v110, v110
	v_exp_f32_e32 v111, v111
	v_pk_mul_f32 v[98:99], v[98:99], v[116:117] op_sel_hi:[1,0]
	v_add_f32_e32 v110, 1.0, v110
	v_add_f32_e32 v111, 1.0, v111
	v_rcp_f32_e32 v110, v110
	v_rcp_f32_e32 v111, v111
	s_nop 0
	v_pk_mul_f32 v[108:109], v[108:109], v[110:111]
	s_nop 0
	v_pk_mul_f32 v[106:107], v[106:107], v[108:109]
	s_nop 0
	v_cvt_pk_bf16_f32 v105, v106, v107
	v_mul_f32_e32 v106, 0xbfb8aa3b, v100
	v_mul_f32_e32 v107, 0xbfb8aa3b, v101
	v_exp_f32_e32 v106, v106
	v_exp_f32_e32 v107, v107
	v_add_f32_e32 v106, 1.0, v106
	v_add_f32_e32 v107, 1.0, v107
	v_rcp_f32_e32 v106, v106
	v_rcp_f32_e32 v107, v107
	s_nop 0
	v_pk_mul_f32 v[100:101], v[100:101], v[106:107]
	s_nop 0
	v_pk_mul_f32 v[96:97], v[96:97], v[100:101]
	v_pk_mul_f32 v[100:101], v[102:103], v[116:117] op_sel_hi:[1,0]
	v_cvt_pk_bf16_f32 v106, v96, v97
	v_mul_f32_e32 v102, 0xbfb8aa3b, v100
	v_mul_f32_e32 v103, 0xbfb8aa3b, v101
	v_exp_f32_e32 v102, v102
	v_exp_f32_e32 v103, v103
	v_mad_i64_i32 v[96:97], s[0:1], v167, s82, v[112:113]
	v_add_f32_e32 v102, 1.0, v102
	v_add_f32_e32 v103, 1.0, v103
	v_rcp_f32_e32 v102, v102
	v_rcp_f32_e32 v103, v103
	v_lshl_add_u64 v[96:97], v[96:97], 0, v[114:115]
	v_pk_mul_f32 v[100:101], v[100:101], v[102:103]
	s_nop 0
	v_pk_mul_f32 v[98:99], v[98:99], v[100:101]
	s_nop 0
	v_cvt_pk_bf16_f32 v107, v98, v99
	global_store_dwordx4 v[96:97], v[104:107], off sc1
	v_ffbh_u32_e32 v96, v149
	v_min_u32_e32 v98, 32, v96
	v_lshlrev_b64 v[96:97], v98, v[148:149]
	v_min_u32_e32 v96, 1, v96
	v_or_b32_e32 v96, v97, v96
	v_cvt_f32_u32_e32 v96, v96
	v_sub_u32_e32 v97, 32, v98
	v_ldexp_f32 v96, v96, v97
	v_fmamk_f32 v96, v96, 0x2e800000, v226
	v_cmp_gt_f32_e32 vcc, s31, v96
	v_mul_f32_e32 v97, 0x4f800000, v96
	s_nop 0
	v_cndmask_b32_e32 v96, v96, v97, vcc
	v_sqrt_f32_e32 v97, v96
	s_nop 0
	v_add_u32_e32 v98, -1, v97
	v_fma_f32 v99, -v98, v97, v96
	v_cmp_ge_f32_e64 s[42:43], 0, v99
	v_add_u32_e32 v99, 1, v97
	s_nop 0
	v_cndmask_b32_e64 v98, v97, v98, s[42:43]
	v_fma_f32 v97, -v99, v97, v96
	v_cmp_lt_f32_e64 s[42:43], 0, v97
	s_nop 1
	v_cndmask_b32_e64 v97, v98, v99, s[42:43]
	v_mul_f32_e32 v98, 0x37800000, v97
	v_cndmask_b32_e32 v97, v97, v98, vcc
	v_cmp_class_f32_e32 vcc, v96, v227
	s_nop 1
	v_cndmask_b32_e32 v96, v97, v96, vcc
	v_div_scale_f32 v97, s[0:1], v96, v96, 1.0
	v_rcp_f32_e32 v98, v97
	s_nop 0
	v_fma_f32 v99, -v97, v98, 1.0
	v_fmac_f32_e32 v98, v99, v98
	v_div_scale_f32 v99, vcc, 1.0, v96, 1.0
	v_mul_f32_e32 v100, v99, v98
	v_fma_f32 v101, -v97, v100, v99
	v_fmac_f32_e32 v100, v101, v98
	v_fma_f32 v97, -v97, v100, v99
	v_div_fmas_f32 v97, v97, v98, v100
	v_div_fixup_f32 v96, v97, v96, 1.0
	v_pk_mul_f32 v[92:93], v[92:93], v[96:97] op_sel_hi:[1,0]
	s_nop 0
	v_mul_f32_e32 v97, 0xbfb8aa3b, v92
	v_exp_f32_e32 v97, v97
	s_nop 0
	v_add_f32_e32 v97, 1.0, v97
	v_rcp_f32_e32 v98, v97
	v_mul_f32_e32 v97, 0xbfb8aa3b, v93
	v_exp_f32_e32 v97, v97
	s_nop 0
	v_add_f32_e32 v97, 1.0, v97
	v_rcp_f32_e32 v99, v97
	v_pk_mul_f32 v[88:89], v[88:89], v[96:97] op_sel_hi:[1,0]
	v_pk_mul_f32 v[90:91], v[90:91], v[96:97] op_sel_hi:[1,0]
	v_pk_mul_f32 v[84:85], v[84:85], v[96:97] op_sel_hi:[1,0]
	v_pk_mul_f32 v[92:93], v[92:93], v[98:99]
	v_pk_mul_f32 v[80:81], v[80:81], v[96:97] op_sel_hi:[1,0]
	v_pk_mul_f32 v[88:89], v[88:89], v[92:93]
	v_pk_mul_f32 v[92:93], v[94:95], v[96:97] op_sel_hi:[1,0]
	v_cvt_pk_bf16_f32 v88, v88, v89
	v_mul_f32_e32 v94, 0xbfb8aa3b, v92
	v_mul_f32_e32 v95, 0xbfb8aa3b, v93
	v_exp_f32_e32 v94, v94
	v_exp_f32_e32 v95, v95
	v_pk_mul_f32 v[82:83], v[82:83], v[96:97] op_sel_hi:[1,0]
	v_add_f32_e32 v94, 1.0, v94
	v_add_f32_e32 v95, 1.0, v95
	v_rcp_f32_e32 v94, v94
	v_rcp_f32_e32 v95, v95
	s_nop 0
	v_pk_mul_f32 v[92:93], v[92:93], v[94:95]
	s_nop 0
	v_pk_mul_f32 v[90:91], v[90:91], v[92:93]
	s_nop 0
	v_cvt_pk_bf16_f32 v89, v90, v91
	v_mul_f32_e32 v90, 0xbfb8aa3b, v84
	v_mul_f32_e32 v91, 0xbfb8aa3b, v85
	v_exp_f32_e32 v90, v90
	v_exp_f32_e32 v91, v91
	v_add_f32_e32 v90, 1.0, v90
	v_add_f32_e32 v91, 1.0, v91
	v_rcp_f32_e32 v90, v90
	v_rcp_f32_e32 v91, v91
	s_nop 0
	v_pk_mul_f32 v[84:85], v[84:85], v[90:91]
	s_nop 0
	v_pk_mul_f32 v[80:81], v[80:81], v[84:85]
	v_pk_mul_f32 v[84:85], v[86:87], v[96:97] op_sel_hi:[1,0]
	v_cvt_pk_bf16_f32 v90, v80, v81
	v_mul_f32_e32 v86, 0xbfb8aa3b, v84
	v_mul_f32_e32 v87, 0xbfb8aa3b, v85
	v_exp_f32_e32 v86, v86
	v_exp_f32_e32 v87, v87
	v_mad_i64_i32 v[80:81], s[0:1], v166, s82, v[112:113]
	v_add_f32_e32 v86, 1.0, v86
	v_add_f32_e32 v87, 1.0, v87
; __device__ __forceinline__ unsigned cvtpk(float lo, float hi) { f32x2_t v = {lo, hi}; bf16x2_t b = __builtin_convertvector(v, bf16x2_t); return __builtin_bit_cast(unsigned, b); }
; __device__ __forceinline__ float ss_rs(u64 v) { return 1.f / sqrtf((float)v * (SSFI / 1024.f) + 1e-6f); }
;     __device__ __forceinline__ void operator()(const Acc& acc, const Unit& u, int wr, int wc, int fr, int fq) const {
;     ...
;                 const int row = row0 + ai * HALF + m * 16; const float rs = ss_rs(sv[ai][m]);
;                 unsigned w[4];
; #pragma unroll
;                 for (int n = 0; n < 2; ++n) {
;                     const f32x4 gv = acc[ai][0][m][n] * rs, uv = acc[ai][1][m][n] * rs; float h[4];
; #pragma unroll
;                     for (int e = 0; e < 4; ++e) { const float gg = gv[e]; h[e] = gg * __builtin_amdgcn_rcpf(1.f + __builtin_amdgcn_exp2f(-1.4426950408889634f * gg)) * uv[e]; }
;                     w[2 * n] = cvtpk(h[0], h[1]); w[2 * n + 1] = cvtpk(h[2], h[3]);
;                 }
;                 *(u32x4*)(O + (size_t)row * DFF + col0) = (u32x4){w[0], w[1], w[2], w[3]};
	v_rcp_f32_e32 v86, v86
	v_rcp_f32_e32 v87, v87
	v_lshl_add_u64 v[80:81], v[80:81], 0, v[114:115]
	v_pk_mul_f32 v[84:85], v[84:85], v[86:87]
	s_nop 0
	v_pk_mul_f32 v[82:83], v[82:83], v[84:85]
	s_nop 0
	v_cvt_pk_bf16_f32 v91, v82, v83
	global_store_dwordx4 v[80:81], v[88:91], off sc1
	v_ffbh_u32_e32 v80, v147
	v_min_u32_e32 v82, 32, v80
	v_lshlrev_b64 v[80:81], v82, v[146:147]
	v_min_u32_e32 v80, 1, v80
	v_or_b32_e32 v80, v81, v80
	v_cvt_f32_u32_e32 v80, v80
	v_sub_u32_e32 v81, 32, v82
	v_ldexp_f32 v80, v80, v81
	v_fmamk_f32 v80, v80, 0x2e800000, v226
	v_cmp_gt_f32_e32 vcc, s31, v80
	v_mul_f32_e32 v81, 0x4f800000, v80
	s_nop 0
	v_cndmask_b32_e32 v80, v80, v81, vcc
	v_sqrt_f32_e32 v81, v80
	s_nop 0
	v_add_u32_e32 v82, -1, v81
	v_fma_f32 v83, -v82, v81, v80
	v_cmp_ge_f32_e64 s[42:43], 0, v83
	v_add_u32_e32 v83, 1, v81
	s_nop 0
	v_cndmask_b32_e64 v82, v81, v82, s[42:43]
	v_fma_f32 v81, -v83, v81, v80
	v_cmp_lt_f32_e64 s[42:43], 0, v81
	s_nop 1
	v_cndmask_b32_e64 v81, v82, v83, s[42:43]
	v_mul_f32_e32 v82, 0x37800000, v81
	v_cndmask_b32_e32 v81, v81, v82, vcc
	v_cmp_class_f32_e32 vcc, v80, v227
	s_nop 1
	v_cndmask_b32_e32 v80, v81, v80, vcc
	v_div_scale_f32 v81, s[0:1], v80, v80, 1.0
	v_rcp_f32_e32 v82, v81
	s_nop 0
	v_fma_f32 v83, -v81, v82, 1.0
	v_fmac_f32_e32 v82, v83, v82
	v_div_scale_f32 v83, vcc, 1.0, v80, 1.0
	v_mul_f32_e32 v84, v83, v82
	v_fma_f32 v85, -v81, v84, v83
	v_fmac_f32_e32 v84, v85, v82
	v_fma_f32 v81, -v81, v84, v83
	v_div_fmas_f32 v81, v81, v82, v84
	v_div_fixup_f32 v80, v81, v80, 1.0
	v_pk_mul_f32 v[76:77], v[76:77], v[80:81] op_sel_hi:[1,0]
	s_nop 0
	v_mul_f32_e32 v81, 0xbfb8aa3b, v76
	v_exp_f32_e32 v81, v81
	s_nop 0
	v_add_f32_e32 v81, 1.0, v81
	v_rcp_f32_e32 v82, v81
	v_mul_f32_e32 v81, 0xbfb8aa3b, v77
	v_exp_f32_e32 v81, v81
	s_nop 0
	v_add_f32_e32 v81, 1.0, v81
	v_rcp_f32_e32 v83, v81
	v_pk_mul_f32 v[72:73], v[72:73], v[80:81] op_sel_hi:[1,0]
	v_pk_mul_f32 v[74:75], v[74:75], v[80:81] op_sel_hi:[1,0]
	v_pk_mul_f32 v[68:69], v[68:69], v[80:81] op_sel_hi:[1,0]
	v_pk_mul_f32 v[76:77], v[76:77], v[82:83]
	v_pk_mul_f32 v[64:65], v[64:65], v[80:81] op_sel_hi:[1,0]
	v_pk_mul_f32 v[72:73], v[72:73], v[76:77]
	v_pk_mul_f32 v[76:77], v[78:79], v[80:81] op_sel_hi:[1,0]
	v_cvt_pk_bf16_f32 v72, v72, v73
	v_mul_f32_e32 v78, 0xbfb8aa3b, v76
	v_mul_f32_e32 v79, 0xbfb8aa3b, v77
	v_exp_f32_e32 v78, v78
	v_exp_f32_e32 v79, v79
	v_pk_mul_f32 v[66:67], v[66:67], v[80:81] op_sel_hi:[1,0]
	v_add_f32_e32 v78, 1.0, v78
	v_add_f32_e32 v79, 1.0, v79
	v_rcp_f32_e32 v78, v78
	v_rcp_f32_e32 v79, v79
	s_nop 0
	v_pk_mul_f32 v[76:77], v[76:77], v[78:79]
	s_nop 0
	v_pk_mul_f32 v[74:75], v[74:75], v[76:77]
	s_nop 0
	v_cvt_pk_bf16_f32 v73, v74, v75
	v_mul_f32_e32 v74, 0xbfb8aa3b, v68
	v_mul_f32_e32 v75, 0xbfb8aa3b, v69
	v_exp_f32_e32 v74, v74
	v_exp_f32_e32 v75, v75
	v_add_f32_e32 v74, 1.0, v74
	v_add_f32_e32 v75, 1.0, v75
	v_rcp_f32_e32 v74, v74
	v_rcp_f32_e32 v75, v75
	s_nop 0
	v_pk_mul_f32 v[68:69], v[68:69], v[74:75]
	s_nop 0
	v_pk_mul_f32 v[64:65], v[64:65], v[68:69]
	v_pk_mul_f32 v[68:69], v[70:71], v[80:81] op_sel_hi:[1,0]
	v_cvt_pk_bf16_f32 v74, v64, v65
	v_mul_f32_e32 v70, 0xbfb8aa3b, v68
	v_mul_f32_e32 v71, 0xbfb8aa3b, v69
	v_exp_f32_e32 v70, v70
	v_exp_f32_e32 v71, v71
	v_mad_i64_i32 v[64:65], s[0:1], v165, s82, v[112:113]
	v_add_f32_e32 v70, 1.0, v70
	v_add_f32_e32 v71, 1.0, v71
	v_rcp_f32_e32 v70, v70
	v_rcp_f32_e32 v71, v71
	v_lshl_add_u64 v[64:65], v[64:65], 0, v[114:115]
	v_pk_mul_f32 v[68:69], v[68:69], v[70:71]
	s_nop 0
	v_pk_mul_f32 v[66:67], v[66:67], v[68:69]
	s_nop 0
	v_cvt_pk_bf16_f32 v75, v66, v67
	global_store_dwordx4 v[64:65], v[72:75], off sc1
	v_ffbh_u32_e32 v64, v145
	v_min_u32_e32 v66, 32, v64
	v_lshlrev_b64 v[64:65], v66, v[144:145]
	v_min_u32_e32 v64, 1, v64
	v_or_b32_e32 v64, v65, v64
	v_cvt_f32_u32_e32 v64, v64
	v_sub_u32_e32 v65, 32, v66
	v_ldexp_f32 v64, v64, v65
	v_fmamk_f32 v64, v64, 0x2e800000, v226
	v_cmp_gt_f32_e32 vcc, s31, v64
	v_mul_f32_e32 v65, 0x4f800000, v64
	s_nop 0
	v_cndmask_b32_e32 v64, v64, v65, vcc
	v_sqrt_f32_e32 v65, v64
	s_nop 0
	v_add_u32_e32 v66, -1, v65
	v_fma_f32 v67, -v66, v65, v64
	v_cmp_ge_f32_e64 s[42:43], 0, v67
	v_add_u32_e32 v67, 1, v65
	s_nop 0
	v_cndmask_b32_e64 v66, v65, v66, s[42:43]
	v_fma_f32 v65, -v67, v65, v64
	v_cmp_lt_f32_e64 s[42:43], 0, v65
	s_nop 1
	v_cndmask_b32_e64 v65, v66, v67, s[42:43]
	v_mul_f32_e32 v66, 0x37800000, v65
	v_cndmask_b32_e32 v65, v65, v66, vcc
	v_cmp_class_f32_e32 vcc, v64, v227
	s_nop 1
	v_cndmask_b32_e32 v64, v65, v64, vcc
	v_div_scale_f32 v65, s[0:1], v64, v64, 1.0
	v_rcp_f32_e32 v66, v65
	s_nop 0
	v_fma_f32 v67, -v65, v66, 1.0
	v_fmac_f32_e32 v66, v67, v66
	v_div_scale_f32 v67, vcc, 1.0, v64, 1.0
	v_mul_f32_e32 v68, v67, v66
	v_fma_f32 v69, -v65, v68, v67
	v_fmac_f32_e32 v68, v69, v66
	v_fma_f32 v65, -v65, v68, v67
	v_div_fmas_f32 v65, v65, v66, v68
	v_div_fixup_f32 v64, v65, v64, 1.0
	v_pk_mul_f32 v[60:61], v[60:61], v[64:65] op_sel_hi:[1,0]
	s_nop 0
	v_mul_f32_e32 v65, 0xbfb8aa3b, v60
	v_exp_f32_e32 v65, v65
	s_nop 0
	v_add_f32_e32 v65, 1.0, v65
	v_rcp_f32_e32 v66, v65
	v_mul_f32_e32 v65, 0xbfb8aa3b, v61
	v_exp_f32_e32 v65, v65
	s_nop 0
	v_add_f32_e32 v65, 1.0, v65
	v_rcp_f32_e32 v67, v65
	v_pk_mul_f32 v[56:57], v[56:57], v[64:65] op_sel_hi:[1,0]
	v_pk_mul_f32 v[58:59], v[58:59], v[64:65] op_sel_hi:[1,0]
	v_pk_mul_f32 v[52:53], v[52:53], v[64:65] op_sel_hi:[1,0]
	v_pk_mul_f32 v[60:61], v[60:61], v[66:67]
	v_pk_mul_f32 v[48:49], v[48:49], v[64:65] op_sel_hi:[1,0]
	v_pk_mul_f32 v[56:57], v[56:57], v[60:61]
	v_pk_mul_f32 v[60:61], v[62:63], v[64:65] op_sel_hi:[1,0]
	v_cvt_pk_bf16_f32 v56, v56, v57
	v_mul_f32_e32 v62, 0xbfb8aa3b, v60
; __device__ __forceinline__ unsigned cvtpk(float lo, float hi) { f32x2_t v = {lo, hi}; bf16x2_t b = __builtin_convertvector(v, bf16x2_t); return __builtin_bit_cast(unsigned, b); }
; __device__ __forceinline__ float ss_rs(u64 v) { return 1.f / sqrtf((float)v * (SSFI / 1024.f) + 1e-6f); }
;     __device__ __forceinline__ void operator()(const Acc& acc, const Unit& u, int wr, int wc, int fr, int fq) const {
;     ...
;                 const int row = row0 + ai * HALF + m * 16; const float rs = ss_rs(sv[ai][m]);
;                 unsigned w[4];
; #pragma unroll
;                 for (int n = 0; n < 2; ++n) {
;                     const f32x4 gv = acc[ai][0][m][n] * rs, uv = acc[ai][1][m][n] * rs; float h[4];
; #pragma unroll
;                     for (int e = 0; e < 4; ++e) { const float gg = gv[e]; h[e] = gg * __builtin_amdgcn_rcpf(1.f + __builtin_amdgcn_exp2f(-1.4426950408889634f * gg)) * uv[e]; }
;                     w[2 * n] = cvtpk(h[0], h[1]); w[2 * n + 1] = cvtpk(h[2], h[3]);
;                 }
;                 *(u32x4*)(O + (size_t)row * DFF + col0) = (u32x4){w[0], w[1], w[2], w[3]};
	v_mul_f32_e32 v63, 0xbfb8aa3b, v61
	v_exp_f32_e32 v62, v62
	v_exp_f32_e32 v63, v63
	v_pk_mul_f32 v[50:51], v[50:51], v[64:65] op_sel_hi:[1,0]
	v_add_f32_e32 v62, 1.0, v62
	v_add_f32_e32 v63, 1.0, v63
	v_rcp_f32_e32 v62, v62
	v_rcp_f32_e32 v63, v63
	s_nop 0
	v_pk_mul_f32 v[60:61], v[60:61], v[62:63]
	s_nop 0
	v_pk_mul_f32 v[58:59], v[58:59], v[60:61]
	s_nop 0
	v_cvt_pk_bf16_f32 v57, v58, v59
	v_mul_f32_e32 v58, 0xbfb8aa3b, v52
	v_mul_f32_e32 v59, 0xbfb8aa3b, v53
	v_exp_f32_e32 v58, v58
	v_exp_f32_e32 v59, v59
	v_add_f32_e32 v58, 1.0, v58
	v_add_f32_e32 v59, 1.0, v59
	v_rcp_f32_e32 v58, v58
	v_rcp_f32_e32 v59, v59
	s_nop 0
	v_pk_mul_f32 v[52:53], v[52:53], v[58:59]
	s_nop 0
	v_pk_mul_f32 v[48:49], v[48:49], v[52:53]
	v_pk_mul_f32 v[52:53], v[54:55], v[64:65] op_sel_hi:[1,0]
	v_cvt_pk_bf16_f32 v58, v48, v49
	v_mul_f32_e32 v54, 0xbfb8aa3b, v52
	v_mul_f32_e32 v55, 0xbfb8aa3b, v53
	v_exp_f32_e32 v54, v54
	v_exp_f32_e32 v55, v55
	v_mad_i64_i32 v[48:49], s[0:1], v164, s82, v[112:113]
	v_add_f32_e32 v54, 1.0, v54
	v_add_f32_e32 v55, 1.0, v55
	v_rcp_f32_e32 v54, v54
	v_rcp_f32_e32 v55, v55
	v_lshl_add_u64 v[48:49], v[48:49], 0, v[114:115]
	v_pk_mul_f32 v[52:53], v[52:53], v[54:55]
	s_nop 0
	v_pk_mul_f32 v[50:51], v[50:51], v[52:53]
	s_nop 0
	v_cvt_pk_bf16_f32 v59, v50, v51
	global_store_dwordx4 v[48:49], v[56:59], off sc1
	v_ffbh_u32_e32 v48, v143
	v_min_u32_e32 v50, 32, v48
	v_lshlrev_b64 v[48:49], v50, v[142:143]
	v_min_u32_e32 v48, 1, v48
	v_or_b32_e32 v48, v49, v48
	v_cvt_f32_u32_e32 v48, v48
	v_sub_u32_e32 v49, 32, v50
	v_ldexp_f32 v48, v48, v49
	v_fmamk_f32 v48, v48, 0x2e800000, v226
	v_cmp_gt_f32_e32 vcc, s31, v48
	v_mul_f32_e32 v49, 0x4f800000, v48
	s_nop 0
	v_cndmask_b32_e32 v48, v48, v49, vcc
	v_sqrt_f32_e32 v49, v48
	s_nop 0
	v_add_u32_e32 v50, -1, v49
	v_fma_f32 v51, -v50, v49, v48
	v_cmp_ge_f32_e64 s[42:43], 0, v51
	v_add_u32_e32 v51, 1, v49
	s_nop 0
	v_cndmask_b32_e64 v50, v49, v50, s[42:43]
	v_fma_f32 v49, -v51, v49, v48
	v_cmp_lt_f32_e64 s[42:43], 0, v49
	s_nop 1
	v_cndmask_b32_e64 v49, v50, v51, s[42:43]
	v_mul_f32_e32 v50, 0x37800000, v49
	v_cndmask_b32_e32 v49, v49, v50, vcc
	v_cmp_class_f32_e32 vcc, v48, v227
	s_nop 1
	v_cndmask_b32_e32 v48, v49, v48, vcc
	v_div_scale_f32 v49, s[0:1], v48, v48, 1.0
	v_rcp_f32_e32 v50, v49
	s_nop 0
	v_fma_f32 v51, -v49, v50, 1.0
	v_fmac_f32_e32 v50, v51, v50
	v_div_scale_f32 v51, vcc, 1.0, v48, 1.0
	v_mul_f32_e32 v52, v51, v50
	v_fma_f32 v53, -v49, v52, v51
	v_fmac_f32_e32 v52, v53, v50
	v_fma_f32 v49, -v49, v52, v51
	v_div_fmas_f32 v49, v49, v50, v52
	v_div_fixup_f32 v48, v49, v48, 1.0
	v_pk_mul_f32 v[44:45], v[44:45], v[48:49] op_sel_hi:[1,0]
	s_nop 0
	v_mul_f32_e32 v49, 0xbfb8aa3b, v44
	v_exp_f32_e32 v49, v49
	s_nop 0
	v_add_f32_e32 v49, 1.0, v49
	v_rcp_f32_e32 v50, v49
	v_mul_f32_e32 v49, 0xbfb8aa3b, v45
	v_exp_f32_e32 v49, v49
	s_nop 0
	v_add_f32_e32 v49, 1.0, v49
	v_rcp_f32_e32 v51, v49
	v_pk_mul_f32 v[40:41], v[40:41], v[48:49] op_sel_hi:[1,0]
	v_pk_mul_f32 v[42:43], v[42:43], v[48:49] op_sel_hi:[1,0]
	v_pk_mul_f32 v[36:37], v[36:37], v[48:49] op_sel_hi:[1,0]
	v_pk_mul_f32 v[44:45], v[44:45], v[50:51]
	v_pk_mul_f32 v[32:33], v[32:33], v[48:49] op_sel_hi:[1,0]
	v_pk_mul_f32 v[40:41], v[40:41], v[44:45]
	v_pk_mul_f32 v[44:45], v[46:47], v[48:49] op_sel_hi:[1,0]
	v_cvt_pk_bf16_f32 v40, v40, v41
	v_mul_f32_e32 v46, 0xbfb8aa3b, v44
	v_mul_f32_e32 v47, 0xbfb8aa3b, v45
	v_exp_f32_e32 v46, v46
	v_exp_f32_e32 v47, v47
	v_pk_mul_f32 v[34:35], v[34:35], v[48:49] op_sel_hi:[1,0]
	v_add_f32_e32 v46, 1.0, v46
	v_add_f32_e32 v47, 1.0, v47
	v_rcp_f32_e32 v46, v46
	v_rcp_f32_e32 v47, v47
	s_nop 0
	v_pk_mul_f32 v[44:45], v[44:45], v[46:47]
	s_nop 0
	v_pk_mul_f32 v[42:43], v[42:43], v[44:45]
	s_nop 0
	v_cvt_pk_bf16_f32 v41, v42, v43
	v_mul_f32_e32 v42, 0xbfb8aa3b, v36
	v_mul_f32_e32 v43, 0xbfb8aa3b, v37
	v_exp_f32_e32 v42, v42
	v_exp_f32_e32 v43, v43
	v_add_f32_e32 v42, 1.0, v42
	v_add_f32_e32 v43, 1.0, v43
	v_rcp_f32_e32 v42, v42
	v_rcp_f32_e32 v43, v43
	s_nop 0
	v_pk_mul_f32 v[36:37], v[36:37], v[42:43]
	s_nop 0
	v_pk_mul_f32 v[32:33], v[32:33], v[36:37]
	v_pk_mul_f32 v[36:37], v[38:39], v[48:49] op_sel_hi:[1,0]
	v_cvt_pk_bf16_f32 v42, v32, v33
	v_mul_f32_e32 v38, 0xbfb8aa3b, v36
	v_mul_f32_e32 v39, 0xbfb8aa3b, v37
	v_exp_f32_e32 v38, v38
	v_exp_f32_e32 v39, v39
	v_mad_i64_i32 v[32:33], s[0:1], v163, s82, v[112:113]
	v_add_f32_e32 v38, 1.0, v38
	v_add_f32_e32 v39, 1.0, v39
	v_rcp_f32_e32 v38, v38
	v_rcp_f32_e32 v39, v39
	v_lshl_add_u64 v[32:33], v[32:33], 0, v[114:115]
	v_pk_mul_f32 v[36:37], v[36:37], v[38:39]
	s_nop 0
	v_pk_mul_f32 v[34:35], v[34:35], v[36:37]
	s_nop 0
	v_cvt_pk_bf16_f32 v43, v34, v35
	global_store_dwordx4 v[32:33], v[40:43], off sc1
	v_ffbh_u32_e32 v32, v141
	v_min_u32_e32 v34, 32, v32
	v_lshlrev_b64 v[32:33], v34, v[140:141]
	v_min_u32_e32 v32, 1, v32
	v_or_b32_e32 v32, v33, v32
	v_cvt_f32_u32_e32 v32, v32
	v_sub_u32_e32 v33, 32, v34
	v_ldexp_f32 v32, v32, v33
	v_fmamk_f32 v32, v32, 0x2e800000, v226
	v_cmp_gt_f32_e32 vcc, s31, v32
	v_mul_f32_e32 v33, 0x4f800000, v32
	s_nop 0
	v_cndmask_b32_e32 v32, v32, v33, vcc
	v_sqrt_f32_e32 v33, v32
	s_nop 0
	v_add_u32_e32 v34, -1, v33
	v_fma_f32 v35, -v34, v33, v32
	v_cmp_ge_f32_e64 s[42:43], 0, v35
	v_add_u32_e32 v35, 1, v33
	s_nop 0
	v_cndmask_b32_e64 v34, v33, v34, s[42:43]
	v_fma_f32 v33, -v35, v33, v32
	v_cmp_lt_f32_e64 s[42:43], 0, v33
	s_nop 1
	v_cndmask_b32_e64 v33, v34, v35, s[42:43]
	v_mul_f32_e32 v34, 0x37800000, v33
	v_cndmask_b32_e32 v33, v33, v34, vcc
	v_cmp_class_f32_e32 vcc, v32, v227
	s_nop 1
	v_cndmask_b32_e32 v32, v33, v32, vcc
	v_div_scale_f32 v33, s[0:1], v32, v32, 1.0
	v_rcp_f32_e32 v34, v33
	s_nop 0
	v_fma_f32 v35, -v33, v34, 1.0
; __device__ __forceinline__ unsigned cvtpk(float lo, float hi) { f32x2_t v = {lo, hi}; bf16x2_t b = __builtin_convertvector(v, bf16x2_t); return __builtin_bit_cast(unsigned, b); }
; __device__ __forceinline__ float ss_rs(u64 v) { return 1.f / sqrtf((float)v * (SSFI / 1024.f) + 1e-6f); }
; #define PG8_BAR __builtin_amdgcn_s_barrier()
; template <class Epi, bool ALIGN_EPI = true>
; __device__ __forceinline__ void gemm_phase(LAS unsigned char* lds, const Gemm g, const StaticOrder& S, const Epi& E, int wave_k) {
;     ...
;         if (!has_next) break;
; #pragma unroll
;         for (int a = 0; a < 2; ++a)
; #pragma unroll
;             for (int b = 0; b < 2; ++b)
; #pragma unroll
;                 for (int m = 0; m < 4; ++m)
; #pragma unroll
;                     for (int n = 0; n < 2; ++n) acc[a][b][m][n] = (f32x4){0.f, 0.f, 0.f, 0.f};
;         cur = nxt; cA = nA; cB = nB; ++ui;
;         if constexpr (ALIGN_EPI) { if (wr == 1) PG8_BAR; }
;     __device__ __forceinline__ void operator()(const Acc& acc, const Unit& u, int wr, int wc, int fr, int fq) const {
;     ...
;                 const int row = row0 + ai * HALF + m * 16; const float rs = ss_rs(sv[ai][m]);
;                 unsigned w[4];
; #pragma unroll
;                 for (int n = 0; n < 2; ++n) {
;                     const f32x4 gv = acc[ai][0][m][n] * rs, uv = acc[ai][1][m][n] * rs; float h[4];
; #pragma unroll
;                     for (int e = 0; e < 4; ++e) { const float gg = gv[e]; h[e] = gg * __builtin_amdgcn_rcpf(1.f + __builtin_amdgcn_exp2f(-1.4426950408889634f * gg)) * uv[e]; }
;                     w[2 * n] = cvtpk(h[0], h[1]); w[2 * n + 1] = cvtpk(h[2], h[3]);
;                 }
;                 *(u32x4*)(O + (size_t)row * DFF + col0) = (u32x4){w[0], w[1], w[2], w[3]};
	v_fmac_f32_e32 v34, v35, v34
	v_div_scale_f32 v35, vcc, 1.0, v32, 1.0
	v_mul_f32_e32 v36, v35, v34
	v_fma_f32 v37, -v33, v36, v35
	v_fmac_f32_e32 v36, v37, v34
	v_fma_f32 v33, -v33, v36, v35
	v_div_fmas_f32 v33, v33, v34, v36
	v_div_fixup_f32 v32, v33, v32, 1.0
	v_pk_mul_f32 v[28:29], v[28:29], v[32:33] op_sel_hi:[1,0]
	s_nop 0
	v_mul_f32_e32 v33, 0xbfb8aa3b, v28
	v_exp_f32_e32 v33, v33
	s_nop 0
	v_add_f32_e32 v33, 1.0, v33
	v_rcp_f32_e32 v34, v33
	v_mul_f32_e32 v33, 0xbfb8aa3b, v29
	v_exp_f32_e32 v33, v33
	s_nop 0
	v_add_f32_e32 v33, 1.0, v33
	v_rcp_f32_e32 v35, v33
	v_pk_mul_f32 v[24:25], v[24:25], v[32:33] op_sel_hi:[1,0]
	v_pk_mul_f32 v[26:27], v[26:27], v[32:33] op_sel_hi:[1,0]
	v_pk_mul_f32 v[20:21], v[20:21], v[32:33] op_sel_hi:[1,0]
	v_pk_mul_f32 v[28:29], v[28:29], v[34:35]
	v_pk_mul_f32 v[16:17], v[16:17], v[32:33] op_sel_hi:[1,0]
	v_pk_mul_f32 v[24:25], v[24:25], v[28:29]
	v_pk_mul_f32 v[28:29], v[30:31], v[32:33] op_sel_hi:[1,0]
	v_cvt_pk_bf16_f32 v24, v24, v25
	v_mul_f32_e32 v30, 0xbfb8aa3b, v28
	v_mul_f32_e32 v31, 0xbfb8aa3b, v29
	v_exp_f32_e32 v30, v30
	v_exp_f32_e32 v31, v31
	v_pk_mul_f32 v[18:19], v[18:19], v[32:33] op_sel_hi:[1,0]
	v_add_f32_e32 v30, 1.0, v30
	v_add_f32_e32 v31, 1.0, v31
	v_rcp_f32_e32 v30, v30
	v_rcp_f32_e32 v31, v31
	s_nop 0
	v_pk_mul_f32 v[28:29], v[28:29], v[30:31]
	s_nop 0
	v_pk_mul_f32 v[26:27], v[26:27], v[28:29]
	s_nop 0
	v_cvt_pk_bf16_f32 v25, v26, v27
	v_mul_f32_e32 v26, 0xbfb8aa3b, v20
	v_mul_f32_e32 v27, 0xbfb8aa3b, v21
	v_exp_f32_e32 v26, v26
	v_exp_f32_e32 v27, v27
	v_add_f32_e32 v26, 1.0, v26
	v_add_f32_e32 v27, 1.0, v27
	v_rcp_f32_e32 v26, v26
	v_rcp_f32_e32 v27, v27
	s_nop 0
	v_pk_mul_f32 v[20:21], v[20:21], v[26:27]
	s_nop 0
	v_pk_mul_f32 v[16:17], v[16:17], v[20:21]
	v_pk_mul_f32 v[20:21], v[22:23], v[32:33] op_sel_hi:[1,0]
	v_cvt_pk_bf16_f32 v26, v16, v17
	v_mul_f32_e32 v22, 0xbfb8aa3b, v20
	v_mul_f32_e32 v23, 0xbfb8aa3b, v21
	v_exp_f32_e32 v22, v22
	v_exp_f32_e32 v23, v23
	v_mad_i64_i32 v[16:17], s[0:1], v162, s82, v[112:113]
	v_add_f32_e32 v22, 1.0, v22
	v_add_f32_e32 v23, 1.0, v23
	v_rcp_f32_e32 v22, v22
	v_rcp_f32_e32 v23, v23
	v_lshl_add_u64 v[16:17], v[16:17], 0, v[114:115]
	v_pk_mul_f32 v[20:21], v[20:21], v[22:23]
	s_nop 0
	v_pk_mul_f32 v[18:19], v[18:19], v[20:21]
	s_nop 0
	v_cvt_pk_bf16_f32 v27, v18, v19
	global_store_dwordx4 v[16:17], v[24:27], off sc1
	v_ffbh_u32_e32 v16, v139
	v_min_u32_e32 v18, 32, v16
	v_lshlrev_b64 v[16:17], v18, v[138:139]
	v_min_u32_e32 v16, 1, v16
	v_or_b32_e32 v16, v17, v16
	v_cvt_f32_u32_e32 v16, v16
	v_sub_u32_e32 v17, 32, v18
	v_ldexp_f32 v16, v16, v17
	v_fmamk_f32 v16, v16, 0x2e800000, v226
	v_cmp_gt_f32_e32 vcc, s31, v16
	v_mul_f32_e32 v17, 0x4f800000, v16
	s_nop 0
	v_cndmask_b32_e32 v16, v16, v17, vcc
	v_sqrt_f32_e32 v17, v16
	s_nop 0
	v_add_u32_e32 v18, -1, v17
	v_fma_f32 v19, -v18, v17, v16
	v_cmp_ge_f32_e64 s[42:43], 0, v19
	v_add_u32_e32 v19, 1, v17
	s_nop 0
	v_cndmask_b32_e64 v18, v17, v18, s[42:43]
	v_fma_f32 v17, -v19, v17, v16
	v_cmp_lt_f32_e64 s[42:43], 0, v17
	s_nop 1
	v_cndmask_b32_e64 v17, v18, v19, s[42:43]
	v_mul_f32_e32 v18, 0x37800000, v17
	v_cndmask_b32_e32 v17, v17, v18, vcc
	v_cmp_class_f32_e32 vcc, v16, v227
	s_nop 1
	v_cndmask_b32_e32 v16, v17, v16, vcc
	v_div_scale_f32 v17, s[0:1], v16, v16, 1.0
	v_rcp_f32_e32 v18, v17
	s_nop 0
	v_fma_f32 v19, -v17, v18, 1.0
	v_fmac_f32_e32 v18, v19, v18
	v_div_scale_f32 v19, vcc, 1.0, v16, 1.0
	v_mul_f32_e32 v20, v19, v18
	v_fma_f32 v21, -v17, v20, v19
	v_fmac_f32_e32 v20, v21, v18
	v_fma_f32 v17, -v17, v20, v19
	v_div_fmas_f32 v17, v17, v18, v20
	v_div_fixup_f32 v16, v17, v16, 1.0
	v_pk_mul_f32 v[12:13], v[12:13], v[16:17] op_sel_hi:[1,0]
	s_andn2_b64 vcc, exec, s[40:41]
	v_mul_f32_e32 v17, 0xbfb8aa3b, v12
	v_exp_f32_e32 v17, v17
	s_nop 0
	v_add_f32_e32 v17, 1.0, v17
	v_rcp_f32_e32 v18, v17
	v_mul_f32_e32 v17, 0xbfb8aa3b, v13
	v_exp_f32_e32 v17, v17
	s_nop 0
	v_add_f32_e32 v17, 1.0, v17
	v_rcp_f32_e32 v19, v17
	v_pk_mul_f32 v[8:9], v[8:9], v[16:17] op_sel_hi:[1,0]
	v_pk_mul_f32 v[10:11], v[10:11], v[16:17] op_sel_hi:[1,0]
	v_pk_mul_f32 v[4:5], v[4:5], v[16:17] op_sel_hi:[1,0]
	v_pk_mul_f32 v[12:13], v[12:13], v[18:19]
	v_pk_mul_f32 v[0:1], v[0:1], v[16:17] op_sel_hi:[1,0]
	v_pk_mul_f32 v[8:9], v[8:9], v[12:13]
	v_pk_mul_f32 v[12:13], v[14:15], v[16:17] op_sel_hi:[1,0]
	v_cvt_pk_bf16_f32 v8, v8, v9
	v_mul_f32_e32 v14, 0xbfb8aa3b, v12
	v_mul_f32_e32 v15, 0xbfb8aa3b, v13
	v_exp_f32_e32 v14, v14
	v_exp_f32_e32 v15, v15
	v_pk_mul_f32 v[2:3], v[2:3], v[16:17] op_sel_hi:[1,0]
	v_add_f32_e32 v14, 1.0, v14
	v_add_f32_e32 v15, 1.0, v15
	v_rcp_f32_e32 v14, v14
	v_rcp_f32_e32 v15, v15
	s_nop 0
	v_pk_mul_f32 v[12:13], v[12:13], v[14:15]
	s_nop 0
	v_pk_mul_f32 v[10:11], v[10:11], v[12:13]
	s_nop 0
	v_cvt_pk_bf16_f32 v9, v10, v11
	v_mul_f32_e32 v10, 0xbfb8aa3b, v4
	v_mul_f32_e32 v11, 0xbfb8aa3b, v5
	v_exp_f32_e32 v10, v10
	v_exp_f32_e32 v11, v11
	v_add_f32_e32 v10, 1.0, v10
	v_add_f32_e32 v11, 1.0, v11
	v_rcp_f32_e32 v10, v10
	v_rcp_f32_e32 v11, v11
	s_nop 0
	v_pk_mul_f32 v[4:5], v[4:5], v[10:11]
	s_nop 0
	v_pk_mul_f32 v[0:1], v[0:1], v[4:5]
	v_pk_mul_f32 v[4:5], v[6:7], v[16:17] op_sel_hi:[1,0]
	v_cvt_pk_bf16_f32 v10, v0, v1
	v_mul_f32_e32 v6, 0xbfb8aa3b, v4
	v_mul_f32_e32 v7, 0xbfb8aa3b, v5
	v_exp_f32_e32 v6, v6
	v_exp_f32_e32 v7, v7
	v_mad_i64_i32 v[0:1], s[0:1], v153, s82, v[112:113]
	v_add_f32_e32 v6, 1.0, v6
	v_add_f32_e32 v7, 1.0, v7
	v_rcp_f32_e32 v6, v6
	v_rcp_f32_e32 v7, v7
	v_lshl_add_u64 v[0:1], v[0:1], 0, v[114:115]
	s_mov_b64 s[0:1], -1
	v_pk_mul_f32 v[4:5], v[4:5], v[6:7]
	s_nop 0
	v_pk_mul_f32 v[2:3], v[2:3], v[4:5]
	s_nop 0
	v_cvt_pk_bf16_f32 v11, v2, v3
	global_store_dwordx4 v[0:1], v[8:11], off sc1
	s_cbranch_vccnz .LBB0_77
	s_andn2_b64 vcc, exec, s[14:15]
	s_cbranch_vccnz .LBB0_76
	s_barrier
	s_branch .LBB0_76

; __device__ __forceinline__ unsigned cvtpk(float lo, float hi) { f32x2_t v = {lo, hi}; bf16x2_t b = __builtin_convertvector(v, bf16x2_t); return __builtin_bit_cast(unsigned, b); }
; __device__ __forceinline__ float ss_rs(u64 v) { return 1.f / sqrtf((float)v * (SSFI / 1024.f) + 1e-6f); }
;     __device__ __forceinline__ void operator()(const Acc& acc, const Unit& u, int wr, int wc, int fr, int fq) const {
;         const int row0 = u.pm * BM + wr * 64 + fr, col0 = u.pn * 128 + wc * 32 + 8 * fq;
;         u64 sv[2][4];
; #pragma unroll
;         for (int ai = 0; ai < 2; ++ai)
; #pragma unroll
;             for (int m = 0; m < 4; ++m) sv[ai][m] = SS[row0 + ai * HALF + m * 16];
; #pragma unroll
;         for (int ai = 0; ai < 2; ++ai)
; #pragma unroll
;             for (int m = 0; m < 4; ++m) {
;                 const int row = row0 + ai * HALF + m * 16; const float rs = ss_rs(sv[ai][m]);
;                 unsigned w[4];
; #pragma unroll
;                 for (int n = 0; n < 2; ++n) {
;                     const f32x4 gv = acc[ai][0][m][n] * rs, uv = acc[ai][1][m][n] * rs; float h[4];
; #pragma unroll
;                     for (int e = 0; e < 4; ++e) { const float gg = gv[e]; h[e] = gg * __builtin_amdgcn_rcpf(1.f + __builtin_amdgcn_exp2f(-1.4426950408889634f * gg)) * uv[e]; }
;                     w[2 * n] = cvtpk(h[0], h[1]); w[2 * n + 1] = cvtpk(h[2], h[3]);
;                 }
;                 *(u32x4*)(O + (size_t)row * DFF + col0) = (u32x4){w[0], w[1], w[2], w[3]};
.LBB0_1144:
	v_lshl_add_u32 v152, s0, 8, v156
	v_ashrrev_i32_e32 v153, 31, v152
	v_lshl_add_u64 v[138:139], v[152:153], 3, s[36:37]
	global_load_dwordx2 v[168:169], v[138:139], off
	global_load_dwordx2 v[150:151], v[138:139], off offset:128
	global_load_dwordx2 v[148:149], v[138:139], off offset:256
	global_load_dwordx2 v[146:147], v[138:139], off offset:384
	v_lshl_or_b32 v154, s1, 7, v158
	v_ashrrev_i32_e32 v155, 31, v154
	global_load_dwordx2 v[144:145], v[138:139], off offset:1024
	global_load_dwordx2 v[142:143], v[138:139], off offset:1152
	global_load_dwordx2 v[140:141], v[138:139], off offset:1280
	v_or_b32_e32 v167, 16, v152
	global_load_dwordx2 v[138:139], v[138:139], off offset:1408
	v_or_b32_e32 v166, 32, v152
	v_or_b32_e32 v165, 48, v152
	v_add_u32_e32 v164, 0x80, v152
	v_add_u32_e32 v163, 0x90, v152
	v_add_u32_e32 v162, 0xa0, v152
	v_add_u32_e32 v153, 0xb0, v152
	s_waitcnt vmcnt(0)
	v_ffbh_u32_e32 v170, v169
	v_min_u32_e32 v170, 32, v170
	v_lshlrev_b64 v[168:169], v170, v[168:169]
	v_min_u32_e32 v168, 1, v168
	v_or_b32_e32 v168, v169, v168
	v_cvt_f32_u32_e32 v168, v168
	v_sub_u32_e32 v169, 32, v170
	v_ldexp_f32 v168, v168, v169
	v_fmamk_f32 v168, v168, 0x2e800000, v226
	v_cmp_gt_f32_e32 vcc, s31, v168
	v_mul_f32_e32 v169, 0x4f800000, v168
	s_nop 0
	v_cndmask_b32_e32 v168, v168, v169, vcc
	v_sqrt_f32_e32 v169, v168
	s_nop 0
	v_add_u32_e32 v170, -1, v169
	v_fma_f32 v171, -v170, v169, v168
	v_cmp_ge_f32_e64 s[44:45], 0, v171
	v_add_u32_e32 v171, 1, v169
	s_nop 0
	v_cndmask_b32_e64 v170, v169, v170, s[44:45]
	v_fma_f32 v169, -v171, v169, v168
	v_cmp_lt_f32_e64 s[44:45], 0, v169
	s_nop 1
	v_cndmask_b32_e64 v169, v170, v171, s[44:45]
	v_mul_f32_e32 v170, 0x37800000, v169
	v_cndmask_b32_e32 v169, v169, v170, vcc
	v_cmp_class_f32_e32 vcc, v168, v227
	s_nop 1
	v_cndmask_b32_e32 v168, v169, v168, vcc
	v_div_scale_f32 v169, s[0:1], v168, v168, 1.0
	v_rcp_f32_e32 v170, v169
	s_nop 0
	v_fma_f32 v171, -v169, v170, 1.0
	v_fmac_f32_e32 v170, v171, v170
	v_div_scale_f32 v171, vcc, 1.0, v168, 1.0
	v_mul_f32_e32 v172, v171, v170
	v_fma_f32 v173, -v169, v172, v171
	v_fmac_f32_e32 v172, v173, v170
	v_fma_f32 v169, -v169, v172, v171
	v_div_fmas_f32 v169, v169, v170, v172
	v_div_fixup_f32 v168, v169, v168, 1.0
	v_pk_mul_f32 v[124:125], v[124:125], v[168:169] op_sel_hi:[1,0]
	s_nop 0
	v_mul_f32_e32 v169, 0xbfb8aa3b, v124
	v_exp_f32_e32 v169, v169
	s_nop 0
	v_add_f32_e32 v169, 1.0, v169
	v_rcp_f32_e32 v170, v169
	v_mul_f32_e32 v169, 0xbfb8aa3b, v125
	v_exp_f32_e32 v169, v169
	s_nop 0
	v_add_f32_e32 v169, 1.0, v169
	v_rcp_f32_e32 v171, v169
	v_pk_mul_f32 v[116:117], v[116:117], v[168:169] op_sel_hi:[1,0]
	v_pk_mul_f32 v[118:119], v[118:119], v[168:169] op_sel_hi:[1,0]
	v_pk_mul_f32 v[112:113], v[112:113], v[168:169] op_sel_hi:[1,0]
	v_pk_mul_f32 v[124:125], v[124:125], v[170:171]
	v_pk_mul_f32 v[114:115], v[114:115], v[168:169] op_sel_hi:[1,0]
	v_pk_mul_f32 v[116:117], v[116:117], v[124:125]
	v_pk_mul_f32 v[124:125], v[126:127], v[168:169] op_sel_hi:[1,0]
	v_cvt_pk_bf16_f32 v116, v116, v117
	v_mul_f32_e32 v126, 0xbfb8aa3b, v124
	v_mul_f32_e32 v127, 0xbfb8aa3b, v125
	v_exp_f32_e32 v126, v126
	v_exp_f32_e32 v127, v127
	v_add_f32_e32 v126, 1.0, v126
	v_add_f32_e32 v127, 1.0, v127
	v_rcp_f32_e32 v126, v126
	v_rcp_f32_e32 v127, v127
	s_nop 0
	v_pk_mul_f32 v[124:125], v[124:125], v[126:127]
	s_nop 0
	v_pk_mul_f32 v[118:119], v[118:119], v[124:125]
	s_nop 0
	v_cvt_pk_bf16_f32 v117, v118, v119
	v_pk_mul_f32 v[118:119], v[120:121], v[168:169] op_sel_hi:[1,0]
	s_nop 0
	v_mul_f32_e32 v120, 0xbfb8aa3b, v118
	v_mul_f32_e32 v121, 0xbfb8aa3b, v119
	v_exp_f32_e32 v120, v120
	v_exp_f32_e32 v121, v121
	v_add_f32_e32 v120, 1.0, v120
	v_add_f32_e32 v121, 1.0, v121
	v_rcp_f32_e32 v120, v120
	v_rcp_f32_e32 v121, v121
	s_nop 0
	v_pk_mul_f32 v[118:119], v[118:119], v[120:121]
	s_nop 0
	v_pk_mul_f32 v[112:113], v[112:113], v[118:119]
	v_pk_mul_f32 v[118:119], v[122:123], v[168:169] op_sel_hi:[1,0]
	s_nop 0
	v_mul_f32_e32 v120, 0xbfb8aa3b, v118
	v_mul_f32_e32 v121, 0xbfb8aa3b, v119
	v_exp_f32_e32 v120, v120
	v_exp_f32_e32 v121, v121
	v_add_f32_e32 v120, 1.0, v120
	v_add_f32_e32 v121, 1.0, v121
	v_rcp_f32_e32 v120, v120
	v_rcp_f32_e32 v121, v121
	s_nop 0
	v_pk_mul_f32 v[118:119], v[118:119], v[120:121]
	s_nop 0
	v_pk_mul_f32 v[114:115], v[114:115], v[118:119]
	v_cvt_pk_bf16_f32 v118, v112, v113
	v_mov_b64_e32 v[112:113], s[34:35]
	v_cvt_pk_bf16_f32 v119, v114, v115
	v_mad_i64_i32 v[120:121], s[0:1], v152, s82, v[112:113]
	v_lshlrev_b64 v[114:115], 1, v[154:155]
	v_lshl_add_u64 v[120:121], v[120:121], 0, v[114:115]
	global_store_dwordx4 v[120:121], v[116:119], off sc1
	s_nop 1
	v_ffbh_u32_e32 v116, v151
	v_min_u32_e32 v118, 32, v116
	v_lshlrev_b64 v[116:117], v118, v[150:151]
	v_min_u32_e32 v116, 1, v116
	v_or_b32_e32 v116, v117, v116
	v_cvt_f32_u32_e32 v116, v116
	v_sub_u32_e32 v117, 32, v118
	v_ldexp_f32 v116, v116, v117
	v_fmamk_f32 v116, v116, 0x2e800000, v226
	v_cmp_gt_f32_e32 vcc, s31, v116
	v_mul_f32_e32 v117, 0x4f800000, v116
	s_nop 0
	v_cndmask_b32_e32 v116, v116, v117, vcc
	v_sqrt_f32_e32 v117, v116
	s_nop 0
	v_add_u32_e32 v118, -1, v117
	v_fma_f32 v119, -v118, v117, v116
	v_cmp_ge_f32_e64 s[44:45], 0, v119
	v_add_u32_e32 v119, 1, v117
	s_nop 0
	v_cndmask_b32_e64 v118, v117, v118, s[44:45]
	v_fma_f32 v117, -v119, v117, v116
	v_cmp_lt_f32_e64 s[44:45], 0, v117
	s_nop 1
	v_cndmask_b32_e64 v117, v118, v119, s[44:45]
	v_mul_f32_e32 v118, 0x37800000, v117
	v_cndmask_b32_e32 v117, v117, v118, vcc
	v_cmp_class_f32_e32 vcc, v116, v227
	s_nop 1
	v_cndmask_b32_e32 v116, v117, v116, vcc
	v_div_scale_f32 v117, s[0:1], v116, v116, 1.0
	v_rcp_f32_e32 v118, v117
	s_nop 0
; __device__ __forceinline__ unsigned cvtpk(float lo, float hi) { f32x2_t v = {lo, hi}; bf16x2_t b = __builtin_convertvector(v, bf16x2_t); return __builtin_bit_cast(unsigned, b); }
; __device__ __forceinline__ float ss_rs(u64 v) { return 1.f / sqrtf((float)v * (SSFI / 1024.f) + 1e-6f); }
;     __device__ __forceinline__ void operator()(const Acc& acc, const Unit& u, int wr, int wc, int fr, int fq) const {
;     ...
;                 const int row = row0 + ai * HALF + m * 16; const float rs = ss_rs(sv[ai][m]);
;                 unsigned w[4];
; #pragma unroll
;                 for (int n = 0; n < 2; ++n) {
;                     const f32x4 gv = acc[ai][0][m][n] * rs, uv = acc[ai][1][m][n] * rs; float h[4];
; #pragma unroll
;                     for (int e = 0; e < 4; ++e) { const float gg = gv[e]; h[e] = gg * __builtin_amdgcn_rcpf(1.f + __builtin_amdgcn_exp2f(-1.4426950408889634f * gg)) * uv[e]; }
;                     w[2 * n] = cvtpk(h[0], h[1]); w[2 * n + 1] = cvtpk(h[2], h[3]);
;                 }
;                 *(u32x4*)(O + (size_t)row * DFF + col0) = (u32x4){w[0], w[1], w[2], w[3]};
	v_fma_f32 v119, -v117, v118, 1.0
	v_fmac_f32_e32 v118, v119, v118
	v_div_scale_f32 v119, vcc, 1.0, v116, 1.0
	v_mul_f32_e32 v120, v119, v118
	v_fma_f32 v121, -v117, v120, v119
	v_fmac_f32_e32 v120, v121, v118
	v_fma_f32 v117, -v117, v120, v119
	v_div_fmas_f32 v117, v117, v118, v120
	v_div_fixup_f32 v116, v117, v116, 1.0
	v_pk_mul_f32 v[108:109], v[108:109], v[116:117] op_sel_hi:[1,0]
	s_nop 0
	v_mul_f32_e32 v117, 0xbfb8aa3b, v108
	v_exp_f32_e32 v117, v117
	s_nop 0
	v_add_f32_e32 v117, 1.0, v117
	v_rcp_f32_e32 v118, v117
	v_mul_f32_e32 v117, 0xbfb8aa3b, v109
	v_exp_f32_e32 v117, v117
	s_nop 0
	v_add_f32_e32 v117, 1.0, v117
	v_rcp_f32_e32 v119, v117
	v_pk_mul_f32 v[104:105], v[104:105], v[116:117] op_sel_hi:[1,0]
	v_pk_mul_f32 v[106:107], v[106:107], v[116:117] op_sel_hi:[1,0]
	v_pk_mul_f32 v[100:101], v[100:101], v[116:117] op_sel_hi:[1,0]
	v_pk_mul_f32 v[108:109], v[108:109], v[118:119]
	v_pk_mul_f32 v[96:97], v[96:97], v[116:117] op_sel_hi:[1,0]
	v_pk_mul_f32 v[104:105], v[104:105], v[108:109]
	v_pk_mul_f32 v[108:109], v[110:111], v[116:117] op_sel_hi:[1,0]
	v_cvt_pk_bf16_f32 v104, v104, v105
	v_mul_f32_e32 v110, 0xbfb8aa3b, v108
	v_mul_f32_e32 v111, 0xbfb8aa3b, v109
	v_exp_f32_e32 v110, v110
	v_exp_f32_e32 v111, v111
	v_pk_mul_f32 v[98:99], v[98:99], v[116:117] op_sel_hi:[1,0]
	v_add_f32_e32 v110, 1.0, v110
	v_add_f32_e32 v111, 1.0, v111
	v_rcp_f32_e32 v110, v110
	v_rcp_f32_e32 v111, v111
	s_nop 0
	v_pk_mul_f32 v[108:109], v[108:109], v[110:111]
	s_nop 0
	v_pk_mul_f32 v[106:107], v[106:107], v[108:109]
	s_nop 0
	v_cvt_pk_bf16_f32 v105, v106, v107
	v_mul_f32_e32 v106, 0xbfb8aa3b, v100
	v_mul_f32_e32 v107, 0xbfb8aa3b, v101
	v_exp_f32_e32 v106, v106
	v_exp_f32_e32 v107, v107
	v_add_f32_e32 v106, 1.0, v106
	v_add_f32_e32 v107, 1.0, v107
	v_rcp_f32_e32 v106, v106
	v_rcp_f32_e32 v107, v107
	s_nop 0
	v_pk_mul_f32 v[100:101], v[100:101], v[106:107]
	s_nop 0
	v_pk_mul_f32 v[96:97], v[96:97], v[100:101]
	v_pk_mul_f32 v[100:101], v[102:103], v[116:117] op_sel_hi:[1,0]
	v_cvt_pk_bf16_f32 v106, v96, v97
	v_mul_f32_e32 v102, 0xbfb8aa3b, v100
	v_mul_f32_e32 v103, 0xbfb8aa3b, v101
	v_exp_f32_e32 v102, v102
	v_exp_f32_e32 v103, v103
	v_mad_i64_i32 v[96:97], s[0:1], v167, s82, v[112:113]
	v_add_f32_e32 v102, 1.0, v102
	v_add_f32_e32 v103, 1.0, v103
	v_rcp_f32_e32 v102, v102
	v_rcp_f32_e32 v103, v103
	v_lshl_add_u64 v[96:97], v[96:97], 0, v[114:115]
	v_pk_mul_f32 v[100:101], v[100:101], v[102:103]
	s_nop 0
	v_pk_mul_f32 v[98:99], v[98:99], v[100:101]
	s_nop 0
	v_cvt_pk_bf16_f32 v107, v98, v99
	global_store_dwordx4 v[96:97], v[104:107], off sc1
	v_ffbh_u32_e32 v96, v149
	v_min_u32_e32 v98, 32, v96
	v_lshlrev_b64 v[96:97], v98, v[148:149]
	v_min_u32_e32 v96, 1, v96
	v_or_b32_e32 v96, v97, v96
	v_cvt_f32_u32_e32 v96, v96
	v_sub_u32_e32 v97, 32, v98
	v_ldexp_f32 v96, v96, v97
	v_fmamk_f32 v96, v96, 0x2e800000, v226
	v_cmp_gt_f32_e32 vcc, s31, v96
	v_mul_f32_e32 v97, 0x4f800000, v96
	s_nop 0
	v_cndmask_b32_e32 v96, v96, v97, vcc
	v_sqrt_f32_e32 v97, v96
	s_nop 0
	v_add_u32_e32 v98, -1, v97
	v_fma_f32 v99, -v98, v97, v96
	v_cmp_ge_f32_e64 s[44:45], 0, v99
	v_add_u32_e32 v99, 1, v97
	s_nop 0
	v_cndmask_b32_e64 v98, v97, v98, s[44:45]
	v_fma_f32 v97, -v99, v97, v96
	v_cmp_lt_f32_e64 s[44:45], 0, v97
	s_nop 1
	v_cndmask_b32_e64 v97, v98, v99, s[44:45]
	v_mul_f32_e32 v98, 0x37800000, v97
	v_cndmask_b32_e32 v97, v97, v98, vcc
	v_cmp_class_f32_e32 vcc, v96, v227
	s_nop 1
	v_cndmask_b32_e32 v96, v97, v96, vcc
	v_div_scale_f32 v97, s[0:1], v96, v96, 1.0
	v_rcp_f32_e32 v98, v97
	s_nop 0
	v_fma_f32 v99, -v97, v98, 1.0
	v_fmac_f32_e32 v98, v99, v98
	v_div_scale_f32 v99, vcc, 1.0, v96, 1.0
	v_mul_f32_e32 v100, v99, v98
	v_fma_f32 v101, -v97, v100, v99
	v_fmac_f32_e32 v100, v101, v98
	v_fma_f32 v97, -v97, v100, v99
	v_div_fmas_f32 v97, v97, v98, v100
	v_div_fixup_f32 v96, v97, v96, 1.0
	v_pk_mul_f32 v[92:93], v[92:93], v[96:97] op_sel_hi:[1,0]
	s_nop 0
	v_mul_f32_e32 v97, 0xbfb8aa3b, v92
	v_exp_f32_e32 v97, v97
	s_nop 0
	v_add_f32_e32 v97, 1.0, v97
	v_rcp_f32_e32 v98, v97
	v_mul_f32_e32 v97, 0xbfb8aa3b, v93
	v_exp_f32_e32 v97, v97
	s_nop 0
	v_add_f32_e32 v97, 1.0, v97
	v_rcp_f32_e32 v99, v97
	v_pk_mul_f32 v[88:89], v[88:89], v[96:97] op_sel_hi:[1,0]
	v_pk_mul_f32 v[90:91], v[90:91], v[96:97] op_sel_hi:[1,0]
	v_pk_mul_f32 v[84:85], v[84:85], v[96:97] op_sel_hi:[1,0]
	v_pk_mul_f32 v[92:93], v[92:93], v[98:99]
	v_pk_mul_f32 v[80:81], v[80:81], v[96:97] op_sel_hi:[1,0]
	v_pk_mul_f32 v[88:89], v[88:89], v[92:93]
	v_pk_mul_f32 v[92:93], v[94:95], v[96:97] op_sel_hi:[1,0]
	v_cvt_pk_bf16_f32 v88, v88, v89
	v_mul_f32_e32 v94, 0xbfb8aa3b, v92
	v_mul_f32_e32 v95, 0xbfb8aa3b, v93
	v_exp_f32_e32 v94, v94
	v_exp_f32_e32 v95, v95
	v_pk_mul_f32 v[82:83], v[82:83], v[96:97] op_sel_hi:[1,0]
	v_add_f32_e32 v94, 1.0, v94
	v_add_f32_e32 v95, 1.0, v95
	v_rcp_f32_e32 v94, v94
	v_rcp_f32_e32 v95, v95
	s_nop 0
	v_pk_mul_f32 v[92:93], v[92:93], v[94:95]
	s_nop 0
	v_pk_mul_f32 v[90:91], v[90:91], v[92:93]
	s_nop 0
	v_cvt_pk_bf16_f32 v89, v90, v91
	v_mul_f32_e32 v90, 0xbfb8aa3b, v84
	v_mul_f32_e32 v91, 0xbfb8aa3b, v85
	v_exp_f32_e32 v90, v90
	v_exp_f32_e32 v91, v91
	v_add_f32_e32 v90, 1.0, v90
	v_add_f32_e32 v91, 1.0, v91
	v_rcp_f32_e32 v90, v90
	v_rcp_f32_e32 v91, v91
	s_nop 0
	v_pk_mul_f32 v[84:85], v[84:85], v[90:91]
	s_nop 0
	v_pk_mul_f32 v[80:81], v[80:81], v[84:85]
	v_pk_mul_f32 v[84:85], v[86:87], v[96:97] op_sel_hi:[1,0]
	v_cvt_pk_bf16_f32 v90, v80, v81
	v_mul_f32_e32 v86, 0xbfb8aa3b, v84
	v_mul_f32_e32 v87, 0xbfb8aa3b, v85
	v_exp_f32_e32 v86, v86
	v_exp_f32_e32 v87, v87
	v_mad_i64_i32 v[80:81], s[0:1], v166, s82, v[112:113]
	v_add_f32_e32 v86, 1.0, v86
	v_add_f32_e32 v87, 1.0, v87
; __device__ __forceinline__ unsigned cvtpk(float lo, float hi) { f32x2_t v = {lo, hi}; bf16x2_t b = __builtin_convertvector(v, bf16x2_t); return __builtin_bit_cast(unsigned, b); }
; __device__ __forceinline__ float ss_rs(u64 v) { return 1.f / sqrtf((float)v * (SSFI / 1024.f) + 1e-6f); }
;     __device__ __forceinline__ void operator()(const Acc& acc, const Unit& u, int wr, int wc, int fr, int fq) const {
;     ...
;                 const int row = row0 + ai * HALF + m * 16; const float rs = ss_rs(sv[ai][m]);
;                 unsigned w[4];
; #pragma unroll
;                 for (int n = 0; n < 2; ++n) {
;                     const f32x4 gv = acc[ai][0][m][n] * rs, uv = acc[ai][1][m][n] * rs; float h[4];
; #pragma unroll
;                     for (int e = 0; e < 4; ++e) { const float gg = gv[e]; h[e] = gg * __builtin_amdgcn_rcpf(1.f + __builtin_amdgcn_exp2f(-1.4426950408889634f * gg)) * uv[e]; }
;                     w[2 * n] = cvtpk(h[0], h[1]); w[2 * n + 1] = cvtpk(h[2], h[3]);
;                 }
;                 *(u32x4*)(O + (size_t)row * DFF + col0) = (u32x4){w[0], w[1], w[2], w[3]};
	v_rcp_f32_e32 v86, v86
	v_rcp_f32_e32 v87, v87
	v_lshl_add_u64 v[80:81], v[80:81], 0, v[114:115]
	v_pk_mul_f32 v[84:85], v[84:85], v[86:87]
	s_nop 0
	v_pk_mul_f32 v[82:83], v[82:83], v[84:85]
	s_nop 0
	v_cvt_pk_bf16_f32 v91, v82, v83
	global_store_dwordx4 v[80:81], v[88:91], off sc1
	v_ffbh_u32_e32 v80, v147
	v_min_u32_e32 v82, 32, v80
	v_lshlrev_b64 v[80:81], v82, v[146:147]
	v_min_u32_e32 v80, 1, v80
	v_or_b32_e32 v80, v81, v80
	v_cvt_f32_u32_e32 v80, v80
	v_sub_u32_e32 v81, 32, v82
	v_ldexp_f32 v80, v80, v81
	v_fmamk_f32 v80, v80, 0x2e800000, v226
	v_cmp_gt_f32_e32 vcc, s31, v80
	v_mul_f32_e32 v81, 0x4f800000, v80
	s_nop 0
	v_cndmask_b32_e32 v80, v80, v81, vcc
	v_sqrt_f32_e32 v81, v80
	s_nop 0
	v_add_u32_e32 v82, -1, v81
	v_fma_f32 v83, -v82, v81, v80
	v_cmp_ge_f32_e64 s[44:45], 0, v83
	v_add_u32_e32 v83, 1, v81
	s_nop 0
	v_cndmask_b32_e64 v82, v81, v82, s[44:45]
	v_fma_f32 v81, -v83, v81, v80
	v_cmp_lt_f32_e64 s[44:45], 0, v81
	s_nop 1
	v_cndmask_b32_e64 v81, v82, v83, s[44:45]
	v_mul_f32_e32 v82, 0x37800000, v81
	v_cndmask_b32_e32 v81, v81, v82, vcc
	v_cmp_class_f32_e32 vcc, v80, v227
	s_nop 1
	v_cndmask_b32_e32 v80, v81, v80, vcc
	v_div_scale_f32 v81, s[0:1], v80, v80, 1.0
	v_rcp_f32_e32 v82, v81
	s_nop 0
	v_fma_f32 v83, -v81, v82, 1.0
	v_fmac_f32_e32 v82, v83, v82
	v_div_scale_f32 v83, vcc, 1.0, v80, 1.0
	v_mul_f32_e32 v84, v83, v82
	v_fma_f32 v85, -v81, v84, v83
	v_fmac_f32_e32 v84, v85, v82
	v_fma_f32 v81, -v81, v84, v83
	v_div_fmas_f32 v81, v81, v82, v84
	v_div_fixup_f32 v80, v81, v80, 1.0
	v_pk_mul_f32 v[76:77], v[76:77], v[80:81] op_sel_hi:[1,0]
	s_nop 0
	v_mul_f32_e32 v81, 0xbfb8aa3b, v76
	v_exp_f32_e32 v81, v81
	s_nop 0
	v_add_f32_e32 v81, 1.0, v81
	v_rcp_f32_e32 v82, v81
	v_mul_f32_e32 v81, 0xbfb8aa3b, v77
	v_exp_f32_e32 v81, v81
	s_nop 0
	v_add_f32_e32 v81, 1.0, v81
	v_rcp_f32_e32 v83, v81
	v_pk_mul_f32 v[72:73], v[72:73], v[80:81] op_sel_hi:[1,0]
	v_pk_mul_f32 v[74:75], v[74:75], v[80:81] op_sel_hi:[1,0]
	v_pk_mul_f32 v[68:69], v[68:69], v[80:81] op_sel_hi:[1,0]
	v_pk_mul_f32 v[76:77], v[76:77], v[82:83]
	v_pk_mul_f32 v[64:65], v[64:65], v[80:81] op_sel_hi:[1,0]
	v_pk_mul_f32 v[72:73], v[72:73], v[76:77]
	v_pk_mul_f32 v[76:77], v[78:79], v[80:81] op_sel_hi:[1,0]
	v_cvt_pk_bf16_f32 v72, v72, v73
	v_mul_f32_e32 v78, 0xbfb8aa3b, v76
	v_mul_f32_e32 v79, 0xbfb8aa3b, v77
	v_exp_f32_e32 v78, v78
	v_exp_f32_e32 v79, v79
	v_pk_mul_f32 v[66:67], v[66:67], v[80:81] op_sel_hi:[1,0]
	v_add_f32_e32 v78, 1.0, v78
	v_add_f32_e32 v79, 1.0, v79
	v_rcp_f32_e32 v78, v78
	v_rcp_f32_e32 v79, v79
	s_nop 0
	v_pk_mul_f32 v[76:77], v[76:77], v[78:79]
	s_nop 0
	v_pk_mul_f32 v[74:75], v[74:75], v[76:77]
	s_nop 0
	v_cvt_pk_bf16_f32 v73, v74, v75
	v_mul_f32_e32 v74, 0xbfb8aa3b, v68
	v_mul_f32_e32 v75, 0xbfb8aa3b, v69
	v_exp_f32_e32 v74, v74
	v_exp_f32_e32 v75, v75
	v_add_f32_e32 v74, 1.0, v74
	v_add_f32_e32 v75, 1.0, v75
	v_rcp_f32_e32 v74, v74
	v_rcp_f32_e32 v75, v75
	s_nop 0
	v_pk_mul_f32 v[68:69], v[68:69], v[74:75]
	s_nop 0
	v_pk_mul_f32 v[64:65], v[64:65], v[68:69]
	v_pk_mul_f32 v[68:69], v[70:71], v[80:81] op_sel_hi:[1,0]
	v_cvt_pk_bf16_f32 v74, v64, v65
	v_mul_f32_e32 v70, 0xbfb8aa3b, v68
	v_mul_f32_e32 v71, 0xbfb8aa3b, v69
	v_exp_f32_e32 v70, v70
	v_exp_f32_e32 v71, v71
	v_mad_i64_i32 v[64:65], s[0:1], v165, s82, v[112:113]
	v_add_f32_e32 v70, 1.0, v70
	v_add_f32_e32 v71, 1.0, v71
	v_rcp_f32_e32 v70, v70
	v_rcp_f32_e32 v71, v71
	v_lshl_add_u64 v[64:65], v[64:65], 0, v[114:115]
	v_pk_mul_f32 v[68:69], v[68:69], v[70:71]
	s_nop 0
	v_pk_mul_f32 v[66:67], v[66:67], v[68:69]
	s_nop 0
	v_cvt_pk_bf16_f32 v75, v66, v67
	global_store_dwordx4 v[64:65], v[72:75], off sc1
	v_ffbh_u32_e32 v64, v145
	v_min_u32_e32 v66, 32, v64
	v_lshlrev_b64 v[64:65], v66, v[144:145]
	v_min_u32_e32 v64, 1, v64
	v_or_b32_e32 v64, v65, v64
	v_cvt_f32_u32_e32 v64, v64
	v_sub_u32_e32 v65, 32, v66
	v_ldexp_f32 v64, v64, v65
	v_fmamk_f32 v64, v64, 0x2e800000, v226
	v_cmp_gt_f32_e32 vcc, s31, v64
	v_mul_f32_e32 v65, 0x4f800000, v64
	s_nop 0
	v_cndmask_b32_e32 v64, v64, v65, vcc
	v_sqrt_f32_e32 v65, v64
	s_nop 0
	v_add_u32_e32 v66, -1, v65
	v_fma_f32 v67, -v66, v65, v64
	v_cmp_ge_f32_e64 s[44:45], 0, v67
	v_add_u32_e32 v67, 1, v65
	s_nop 0
	v_cndmask_b32_e64 v66, v65, v66, s[44:45]
	v_fma_f32 v65, -v67, v65, v64
	v_cmp_lt_f32_e64 s[44:45], 0, v65
	s_nop 1
	v_cndmask_b32_e64 v65, v66, v67, s[44:45]
	v_mul_f32_e32 v66, 0x37800000, v65
	v_cndmask_b32_e32 v65, v65, v66, vcc
	v_cmp_class_f32_e32 vcc, v64, v227
	s_nop 1
	v_cndmask_b32_e32 v64, v65, v64, vcc
	v_div_scale_f32 v65, s[0:1], v64, v64, 1.0
	v_rcp_f32_e32 v66, v65
	s_nop 0
	v_fma_f32 v67, -v65, v66, 1.0
	v_fmac_f32_e32 v66, v67, v66
	v_div_scale_f32 v67, vcc, 1.0, v64, 1.0
	v_mul_f32_e32 v68, v67, v66
	v_fma_f32 v69, -v65, v68, v67
	v_fmac_f32_e32 v68, v69, v66
	v_fma_f32 v65, -v65, v68, v67
	v_div_fmas_f32 v65, v65, v66, v68
	v_div_fixup_f32 v64, v65, v64, 1.0
	v_pk_mul_f32 v[60:61], v[60:61], v[64:65] op_sel_hi:[1,0]
	s_nop 0
	v_mul_f32_e32 v65, 0xbfb8aa3b, v60
	v_exp_f32_e32 v65, v65
	s_nop 0
	v_add_f32_e32 v65, 1.0, v65
	v_rcp_f32_e32 v66, v65
	v_mul_f32_e32 v65, 0xbfb8aa3b, v61
	v_exp_f32_e32 v65, v65
	s_nop 0
	v_add_f32_e32 v65, 1.0, v65
	v_rcp_f32_e32 v67, v65
	v_pk_mul_f32 v[56:57], v[56:57], v[64:65] op_sel_hi:[1,0]
	v_pk_mul_f32 v[58:59], v[58:59], v[64:65] op_sel_hi:[1,0]
	v_pk_mul_f32 v[52:53], v[52:53], v[64:65] op_sel_hi:[1,0]
	v_pk_mul_f32 v[60:61], v[60:61], v[66:67]
	v_pk_mul_f32 v[48:49], v[48:49], v[64:65] op_sel_hi:[1,0]
	v_pk_mul_f32 v[56:57], v[56:57], v[60:61]
	v_pk_mul_f32 v[60:61], v[62:63], v[64:65] op_sel_hi:[1,0]
	v_cvt_pk_bf16_f32 v56, v56, v57
	v_mul_f32_e32 v62, 0xbfb8aa3b, v60
; __device__ __forceinline__ unsigned cvtpk(float lo, float hi) { f32x2_t v = {lo, hi}; bf16x2_t b = __builtin_convertvector(v, bf16x2_t); return __builtin_bit_cast(unsigned, b); }
; __device__ __forceinline__ float ss_rs(u64 v) { return 1.f / sqrtf((float)v * (SSFI / 1024.f) + 1e-6f); }
;     __device__ __forceinline__ void operator()(const Acc& acc, const Unit& u, int wr, int wc, int fr, int fq) const {
;     ...
;                 const int row = row0 + ai * HALF + m * 16; const float rs = ss_rs(sv[ai][m]);
;                 unsigned w[4];
; #pragma unroll
;                 for (int n = 0; n < 2; ++n) {
;                     const f32x4 gv = acc[ai][0][m][n] * rs, uv = acc[ai][1][m][n] * rs; float h[4];
; #pragma unroll
;                     for (int e = 0; e < 4; ++e) { const float gg = gv[e]; h[e] = gg * __builtin_amdgcn_rcpf(1.f + __builtin_amdgcn_exp2f(-1.4426950408889634f * gg)) * uv[e]; }
;                     w[2 * n] = cvtpk(h[0], h[1]); w[2 * n + 1] = cvtpk(h[2], h[3]);
;                 }
;                 *(u32x4*)(O + (size_t)row * DFF + col0) = (u32x4){w[0], w[1], w[2], w[3]};
	v_mul_f32_e32 v63, 0xbfb8aa3b, v61
	v_exp_f32_e32 v62, v62
	v_exp_f32_e32 v63, v63
	v_pk_mul_f32 v[50:51], v[50:51], v[64:65] op_sel_hi:[1,0]
	v_add_f32_e32 v62, 1.0, v62
	v_add_f32_e32 v63, 1.0, v63
	v_rcp_f32_e32 v62, v62
	v_rcp_f32_e32 v63, v63
	s_nop 0
	v_pk_mul_f32 v[60:61], v[60:61], v[62:63]
	s_nop 0
	v_pk_mul_f32 v[58:59], v[58:59], v[60:61]
	s_nop 0
	v_cvt_pk_bf16_f32 v57, v58, v59
	v_mul_f32_e32 v58, 0xbfb8aa3b, v52
	v_mul_f32_e32 v59, 0xbfb8aa3b, v53
	v_exp_f32_e32 v58, v58
	v_exp_f32_e32 v59, v59
	v_add_f32_e32 v58, 1.0, v58
	v_add_f32_e32 v59, 1.0, v59
	v_rcp_f32_e32 v58, v58
	v_rcp_f32_e32 v59, v59
	s_nop 0
	v_pk_mul_f32 v[52:53], v[52:53], v[58:59]
	s_nop 0
	v_pk_mul_f32 v[48:49], v[48:49], v[52:53]
	v_pk_mul_f32 v[52:53], v[54:55], v[64:65] op_sel_hi:[1,0]
	v_cvt_pk_bf16_f32 v58, v48, v49
	v_mul_f32_e32 v54, 0xbfb8aa3b, v52
	v_mul_f32_e32 v55, 0xbfb8aa3b, v53
	v_exp_f32_e32 v54, v54
	v_exp_f32_e32 v55, v55
	v_mad_i64_i32 v[48:49], s[0:1], v164, s82, v[112:113]
	v_add_f32_e32 v54, 1.0, v54
	v_add_f32_e32 v55, 1.0, v55
	v_rcp_f32_e32 v54, v54
	v_rcp_f32_e32 v55, v55
	v_lshl_add_u64 v[48:49], v[48:49], 0, v[114:115]
	v_pk_mul_f32 v[52:53], v[52:53], v[54:55]
	s_nop 0
	v_pk_mul_f32 v[50:51], v[50:51], v[52:53]
	s_nop 0
	v_cvt_pk_bf16_f32 v59, v50, v51
	global_store_dwordx4 v[48:49], v[56:59], off sc1
	v_ffbh_u32_e32 v48, v143
	v_min_u32_e32 v50, 32, v48
	v_lshlrev_b64 v[48:49], v50, v[142:143]
	v_min_u32_e32 v48, 1, v48
	v_or_b32_e32 v48, v49, v48
	v_cvt_f32_u32_e32 v48, v48
	v_sub_u32_e32 v49, 32, v50
	v_ldexp_f32 v48, v48, v49
	v_fmamk_f32 v48, v48, 0x2e800000, v226
	v_cmp_gt_f32_e32 vcc, s31, v48
	v_mul_f32_e32 v49, 0x4f800000, v48
	s_nop 0
	v_cndmask_b32_e32 v48, v48, v49, vcc
	v_sqrt_f32_e32 v49, v48
	s_nop 0
	v_add_u32_e32 v50, -1, v49
	v_fma_f32 v51, -v50, v49, v48
	v_cmp_ge_f32_e64 s[44:45], 0, v51
	v_add_u32_e32 v51, 1, v49
	s_nop 0
	v_cndmask_b32_e64 v50, v49, v50, s[44:45]
	v_fma_f32 v49, -v51, v49, v48
	v_cmp_lt_f32_e64 s[44:45], 0, v49
	s_nop 1
	v_cndmask_b32_e64 v49, v50, v51, s[44:45]
	v_mul_f32_e32 v50, 0x37800000, v49
	v_cndmask_b32_e32 v49, v49, v50, vcc
	v_cmp_class_f32_e32 vcc, v48, v227
	s_nop 1
	v_cndmask_b32_e32 v48, v49, v48, vcc
	v_div_scale_f32 v49, s[0:1], v48, v48, 1.0
	v_rcp_f32_e32 v50, v49
	s_nop 0
	v_fma_f32 v51, -v49, v50, 1.0
	v_fmac_f32_e32 v50, v51, v50
	v_div_scale_f32 v51, vcc, 1.0, v48, 1.0
	v_mul_f32_e32 v52, v51, v50
	v_fma_f32 v53, -v49, v52, v51
	v_fmac_f32_e32 v52, v53, v50
	v_fma_f32 v49, -v49, v52, v51
	v_div_fmas_f32 v49, v49, v50, v52
	v_div_fixup_f32 v48, v49, v48, 1.0
	v_pk_mul_f32 v[44:45], v[44:45], v[48:49] op_sel_hi:[1,0]
	s_nop 0
	v_mul_f32_e32 v49, 0xbfb8aa3b, v44
	v_exp_f32_e32 v49, v49
	s_nop 0
	v_add_f32_e32 v49, 1.0, v49
	v_rcp_f32_e32 v50, v49
	v_mul_f32_e32 v49, 0xbfb8aa3b, v45
	v_exp_f32_e32 v49, v49
	s_nop 0
	v_add_f32_e32 v49, 1.0, v49
	v_rcp_f32_e32 v51, v49
	v_pk_mul_f32 v[40:41], v[40:41], v[48:49] op_sel_hi:[1,0]
	v_pk_mul_f32 v[42:43], v[42:43], v[48:49] op_sel_hi:[1,0]
	v_pk_mul_f32 v[36:37], v[36:37], v[48:49] op_sel_hi:[1,0]
	v_pk_mul_f32 v[44:45], v[44:45], v[50:51]
	v_pk_mul_f32 v[32:33], v[32:33], v[48:49] op_sel_hi:[1,0]
	v_pk_mul_f32 v[40:41], v[40:41], v[44:45]
	v_pk_mul_f32 v[44:45], v[46:47], v[48:49] op_sel_hi:[1,0]
	v_cvt_pk_bf16_f32 v40, v40, v41
	v_mul_f32_e32 v46, 0xbfb8aa3b, v44
	v_mul_f32_e32 v47, 0xbfb8aa3b, v45
	v_exp_f32_e32 v46, v46
	v_exp_f32_e32 v47, v47
	v_pk_mul_f32 v[34:35], v[34:35], v[48:49] op_sel_hi:[1,0]
	v_add_f32_e32 v46, 1.0, v46
	v_add_f32_e32 v47, 1.0, v47
	v_rcp_f32_e32 v46, v46
	v_rcp_f32_e32 v47, v47
	s_nop 0
	v_pk_mul_f32 v[44:45], v[44:45], v[46:47]
	s_nop 0
	v_pk_mul_f32 v[42:43], v[42:43], v[44:45]
	s_nop 0
	v_cvt_pk_bf16_f32 v41, v42, v43
	v_mul_f32_e32 v42, 0xbfb8aa3b, v36
	v_mul_f32_e32 v43, 0xbfb8aa3b, v37
	v_exp_f32_e32 v42, v42
	v_exp_f32_e32 v43, v43
	v_add_f32_e32 v42, 1.0, v42
	v_add_f32_e32 v43, 1.0, v43
	v_rcp_f32_e32 v42, v42
	v_rcp_f32_e32 v43, v43
	s_nop 0
	v_pk_mul_f32 v[36:37], v[36:37], v[42:43]
	s_nop 0
	v_pk_mul_f32 v[32:33], v[32:33], v[36:37]
	v_pk_mul_f32 v[36:37], v[38:39], v[48:49] op_sel_hi:[1,0]
	v_cvt_pk_bf16_f32 v42, v32, v33
	v_mul_f32_e32 v38, 0xbfb8aa3b, v36
	v_mul_f32_e32 v39, 0xbfb8aa3b, v37
	v_exp_f32_e32 v38, v38
	v_exp_f32_e32 v39, v39
	v_mad_i64_i32 v[32:33], s[0:1], v163, s82, v[112:113]
	v_add_f32_e32 v38, 1.0, v38
	v_add_f32_e32 v39, 1.0, v39
	v_rcp_f32_e32 v38, v38
	v_rcp_f32_e32 v39, v39
	v_lshl_add_u64 v[32:33], v[32:33], 0, v[114:115]
	v_pk_mul_f32 v[36:37], v[36:37], v[38:39]
	s_nop 0
	v_pk_mul_f32 v[34:35], v[34:35], v[36:37]
	s_nop 0
	v_cvt_pk_bf16_f32 v43, v34, v35
	global_store_dwordx4 v[32:33], v[40:43], off sc1
	v_ffbh_u32_e32 v32, v141
	v_min_u32_e32 v34, 32, v32
	v_lshlrev_b64 v[32:33], v34, v[140:141]
	v_min_u32_e32 v32, 1, v32
	v_or_b32_e32 v32, v33, v32
	v_cvt_f32_u32_e32 v32, v32
	v_sub_u32_e32 v33, 32, v34
	v_ldexp_f32 v32, v32, v33
	v_fmamk_f32 v32, v32, 0x2e800000, v226
	v_cmp_gt_f32_e32 vcc, s31, v32
	v_mul_f32_e32 v33, 0x4f800000, v32
	s_nop 0
	v_cndmask_b32_e32 v32, v32, v33, vcc
	v_sqrt_f32_e32 v33, v32
	s_nop 0
	v_add_u32_e32 v34, -1, v33
	v_fma_f32 v35, -v34, v33, v32
	v_cmp_ge_f32_e64 s[44:45], 0, v35
	v_add_u32_e32 v35, 1, v33
	s_nop 0
	v_cndmask_b32_e64 v34, v33, v34, s[44:45]
	v_fma_f32 v33, -v35, v33, v32
	v_cmp_lt_f32_e64 s[44:45], 0, v33
	s_nop 1
	v_cndmask_b32_e64 v33, v34, v35, s[44:45]
	v_mul_f32_e32 v34, 0x37800000, v33
	v_cndmask_b32_e32 v33, v33, v34, vcc
	v_cmp_class_f32_e32 vcc, v32, v227
	s_nop 1
	v_cndmask_b32_e32 v32, v33, v32, vcc
	v_div_scale_f32 v33, s[0:1], v32, v32, 1.0
	v_rcp_f32_e32 v34, v33
	s_nop 0
	v_fma_f32 v35, -v33, v34, 1.0
; __device__ __forceinline__ unsigned cvtpk(float lo, float hi) { f32x2_t v = {lo, hi}; bf16x2_t b = __builtin_convertvector(v, bf16x2_t); return __builtin_bit_cast(unsigned, b); }
; __device__ __forceinline__ float ss_rs(u64 v) { return 1.f / sqrtf((float)v * (SSFI / 1024.f) + 1e-6f); }
; #define PG8_BAR __builtin_amdgcn_s_barrier()
; template <class Epi, bool ALIGN_EPI = true>
; __device__ __forceinline__ void gemm_phase(LAS unsigned char* lds, const Gemm g, const StaticOrder& S, const Epi& E, int wave_k) {
;     ...
;         if (!has_next) break;
; #pragma unroll
;         for (int a = 0; a < 2; ++a)
; #pragma unroll
;             for (int b = 0; b < 2; ++b)
; #pragma unroll
;                 for (int m = 0; m < 4; ++m)
; #pragma unroll
;                     for (int n = 0; n < 2; ++n) acc[a][b][m][n] = (f32x4){0.f, 0.f, 0.f, 0.f};
;         cur = nxt; cA = nA; cB = nB; ++ui;
;         if constexpr (ALIGN_EPI) { if (wr == 1) PG8_BAR; }
;     __device__ __forceinline__ void operator()(const Acc& acc, const Unit& u, int wr, int wc, int fr, int fq) const {
;     ...
;                 const int row = row0 + ai * HALF + m * 16; const float rs = ss_rs(sv[ai][m]);
;                 unsigned w[4];
; #pragma unroll
;                 for (int n = 0; n < 2; ++n) {
;                     const f32x4 gv = acc[ai][0][m][n] * rs, uv = acc[ai][1][m][n] * rs; float h[4];
; #pragma unroll
;                     for (int e = 0; e < 4; ++e) { const float gg = gv[e]; h[e] = gg * __builtin_amdgcn_rcpf(1.f + __builtin_amdgcn_exp2f(-1.4426950408889634f * gg)) * uv[e]; }
;                     w[2 * n] = cvtpk(h[0], h[1]); w[2 * n + 1] = cvtpk(h[2], h[3]);
;                 }
;                 *(u32x4*)(O + (size_t)row * DFF + col0) = (u32x4){w[0], w[1], w[2], w[3]};
	v_fmac_f32_e32 v34, v35, v34
	v_div_scale_f32 v35, vcc, 1.0, v32, 1.0
	v_mul_f32_e32 v36, v35, v34
	v_fma_f32 v37, -v33, v36, v35
	v_fmac_f32_e32 v36, v37, v34
	v_fma_f32 v33, -v33, v36, v35
	v_div_fmas_f32 v33, v33, v34, v36
	v_div_fixup_f32 v32, v33, v32, 1.0
	v_pk_mul_f32 v[28:29], v[28:29], v[32:33] op_sel_hi:[1,0]
	s_nop 0
	v_mul_f32_e32 v33, 0xbfb8aa3b, v28
	v_exp_f32_e32 v33, v33
	s_nop 0
	v_add_f32_e32 v33, 1.0, v33
	v_rcp_f32_e32 v34, v33
	v_mul_f32_e32 v33, 0xbfb8aa3b, v29
	v_exp_f32_e32 v33, v33
	s_nop 0
	v_add_f32_e32 v33, 1.0, v33
	v_rcp_f32_e32 v35, v33
	v_pk_mul_f32 v[24:25], v[24:25], v[32:33] op_sel_hi:[1,0]
	v_pk_mul_f32 v[26:27], v[26:27], v[32:33] op_sel_hi:[1,0]
	v_pk_mul_f32 v[20:21], v[20:21], v[32:33] op_sel_hi:[1,0]
	v_pk_mul_f32 v[28:29], v[28:29], v[34:35]
	v_pk_mul_f32 v[16:17], v[16:17], v[32:33] op_sel_hi:[1,0]
	v_pk_mul_f32 v[24:25], v[24:25], v[28:29]
	v_pk_mul_f32 v[28:29], v[30:31], v[32:33] op_sel_hi:[1,0]
	v_cvt_pk_bf16_f32 v24, v24, v25
	v_mul_f32_e32 v30, 0xbfb8aa3b, v28
	v_mul_f32_e32 v31, 0xbfb8aa3b, v29
	v_exp_f32_e32 v30, v30
	v_exp_f32_e32 v31, v31
	v_pk_mul_f32 v[18:19], v[18:19], v[32:33] op_sel_hi:[1,0]
	v_add_f32_e32 v30, 1.0, v30
	v_add_f32_e32 v31, 1.0, v31
	v_rcp_f32_e32 v30, v30
	v_rcp_f32_e32 v31, v31
	s_nop 0
	v_pk_mul_f32 v[28:29], v[28:29], v[30:31]
	s_nop 0
	v_pk_mul_f32 v[26:27], v[26:27], v[28:29]
	s_nop 0
	v_cvt_pk_bf16_f32 v25, v26, v27
	v_mul_f32_e32 v26, 0xbfb8aa3b, v20
	v_mul_f32_e32 v27, 0xbfb8aa3b, v21
	v_exp_f32_e32 v26, v26
	v_exp_f32_e32 v27, v27
	v_add_f32_e32 v26, 1.0, v26
	v_add_f32_e32 v27, 1.0, v27
	v_rcp_f32_e32 v26, v26
	v_rcp_f32_e32 v27, v27
	s_nop 0
	v_pk_mul_f32 v[20:21], v[20:21], v[26:27]
	s_nop 0
	v_pk_mul_f32 v[16:17], v[16:17], v[20:21]
	v_pk_mul_f32 v[20:21], v[22:23], v[32:33] op_sel_hi:[1,0]
	v_cvt_pk_bf16_f32 v26, v16, v17
	v_mul_f32_e32 v22, 0xbfb8aa3b, v20
	v_mul_f32_e32 v23, 0xbfb8aa3b, v21
	v_exp_f32_e32 v22, v22
	v_exp_f32_e32 v23, v23
	v_mad_i64_i32 v[16:17], s[0:1], v162, s82, v[112:113]
	v_add_f32_e32 v22, 1.0, v22
	v_add_f32_e32 v23, 1.0, v23
	v_rcp_f32_e32 v22, v22
	v_rcp_f32_e32 v23, v23
	v_lshl_add_u64 v[16:17], v[16:17], 0, v[114:115]
	v_pk_mul_f32 v[20:21], v[20:21], v[22:23]
	s_nop 0
	v_pk_mul_f32 v[18:19], v[18:19], v[20:21]
	s_nop 0
	v_cvt_pk_bf16_f32 v27, v18, v19
	global_store_dwordx4 v[16:17], v[24:27], off sc1
	v_ffbh_u32_e32 v16, v139
	v_min_u32_e32 v18, 32, v16
	v_lshlrev_b64 v[16:17], v18, v[138:139]
	v_min_u32_e32 v16, 1, v16
	v_or_b32_e32 v16, v17, v16
	v_cvt_f32_u32_e32 v16, v16
	v_sub_u32_e32 v17, 32, v18
	v_ldexp_f32 v16, v16, v17
	v_fmamk_f32 v16, v16, 0x2e800000, v226
	v_cmp_gt_f32_e32 vcc, s31, v16
	v_mul_f32_e32 v17, 0x4f800000, v16
	s_nop 0
	v_cndmask_b32_e32 v16, v16, v17, vcc
	v_sqrt_f32_e32 v17, v16
	s_nop 0
	v_add_u32_e32 v18, -1, v17
	v_fma_f32 v19, -v18, v17, v16
	v_cmp_ge_f32_e64 s[44:45], 0, v19
	v_add_u32_e32 v19, 1, v17
	s_nop 0
	v_cndmask_b32_e64 v18, v17, v18, s[44:45]
	v_fma_f32 v17, -v19, v17, v16
	v_cmp_lt_f32_e64 s[44:45], 0, v17
	s_nop 1
	v_cndmask_b32_e64 v17, v18, v19, s[44:45]
	v_mul_f32_e32 v18, 0x37800000, v17
	v_cndmask_b32_e32 v17, v17, v18, vcc
	v_cmp_class_f32_e32 vcc, v16, v227
	s_nop 1
	v_cndmask_b32_e32 v16, v17, v16, vcc
	v_div_scale_f32 v17, s[0:1], v16, v16, 1.0
	v_rcp_f32_e32 v18, v17
	s_nop 0
	v_fma_f32 v19, -v17, v18, 1.0
	v_fmac_f32_e32 v18, v19, v18
	v_div_scale_f32 v19, vcc, 1.0, v16, 1.0
	v_mul_f32_e32 v20, v19, v18
	v_fma_f32 v21, -v17, v20, v19
	v_fmac_f32_e32 v20, v21, v18
	v_fma_f32 v17, -v17, v20, v19
	v_div_fmas_f32 v17, v17, v18, v20
	v_div_fixup_f32 v16, v17, v16, 1.0
	v_pk_mul_f32 v[12:13], v[12:13], v[16:17] op_sel_hi:[1,0]
	s_andn2_b64 vcc, exec, s[42:43]
	v_mul_f32_e32 v17, 0xbfb8aa3b, v12
	v_exp_f32_e32 v17, v17
	s_nop 0
	v_add_f32_e32 v17, 1.0, v17
	v_rcp_f32_e32 v18, v17
	v_mul_f32_e32 v17, 0xbfb8aa3b, v13
	v_exp_f32_e32 v17, v17
	s_nop 0
	v_add_f32_e32 v17, 1.0, v17
	v_rcp_f32_e32 v19, v17
	v_pk_mul_f32 v[8:9], v[8:9], v[16:17] op_sel_hi:[1,0]
	v_pk_mul_f32 v[10:11], v[10:11], v[16:17] op_sel_hi:[1,0]
	v_pk_mul_f32 v[4:5], v[4:5], v[16:17] op_sel_hi:[1,0]
	v_pk_mul_f32 v[12:13], v[12:13], v[18:19]
	v_pk_mul_f32 v[0:1], v[0:1], v[16:17] op_sel_hi:[1,0]
	v_pk_mul_f32 v[8:9], v[8:9], v[12:13]
	v_pk_mul_f32 v[12:13], v[14:15], v[16:17] op_sel_hi:[1,0]
	v_cvt_pk_bf16_f32 v8, v8, v9
	v_mul_f32_e32 v14, 0xbfb8aa3b, v12
	v_mul_f32_e32 v15, 0xbfb8aa3b, v13
	v_exp_f32_e32 v14, v14
	v_exp_f32_e32 v15, v15
	v_pk_mul_f32 v[2:3], v[2:3], v[16:17] op_sel_hi:[1,0]
	v_add_f32_e32 v14, 1.0, v14
	v_add_f32_e32 v15, 1.0, v15
	v_rcp_f32_e32 v14, v14
	v_rcp_f32_e32 v15, v15
	s_nop 0
	v_pk_mul_f32 v[12:13], v[12:13], v[14:15]
	s_nop 0
	v_pk_mul_f32 v[10:11], v[10:11], v[12:13]
	s_nop 0
	v_cvt_pk_bf16_f32 v9, v10, v11
	v_mul_f32_e32 v10, 0xbfb8aa3b, v4
	v_mul_f32_e32 v11, 0xbfb8aa3b, v5
	v_exp_f32_e32 v10, v10
	v_exp_f32_e32 v11, v11
	v_add_f32_e32 v10, 1.0, v10
	v_add_f32_e32 v11, 1.0, v11
	v_rcp_f32_e32 v10, v10
	v_rcp_f32_e32 v11, v11
	s_nop 0
	v_pk_mul_f32 v[4:5], v[4:5], v[10:11]
	s_nop 0
	v_pk_mul_f32 v[0:1], v[0:1], v[4:5]
	v_pk_mul_f32 v[4:5], v[6:7], v[16:17] op_sel_hi:[1,0]
	v_cvt_pk_bf16_f32 v10, v0, v1
	v_mul_f32_e32 v6, 0xbfb8aa3b, v4
	v_mul_f32_e32 v7, 0xbfb8aa3b, v5
	v_exp_f32_e32 v6, v6
	v_exp_f32_e32 v7, v7
	v_mad_i64_i32 v[0:1], s[0:1], v153, s82, v[112:113]
	v_add_f32_e32 v6, 1.0, v6
	v_add_f32_e32 v7, 1.0, v7
	v_rcp_f32_e32 v6, v6
	v_rcp_f32_e32 v7, v7
	v_lshl_add_u64 v[0:1], v[0:1], 0, v[114:115]
	s_mov_b64 s[0:1], -1
	v_pk_mul_f32 v[4:5], v[4:5], v[6:7]
	s_nop 0
	v_pk_mul_f32 v[2:3], v[2:3], v[4:5]
	s_nop 0
	v_cvt_pk_bf16_f32 v11, v2, v3
	global_store_dwordx4 v[0:1], v[8:11], off sc1
	s_cbranch_vccnz .LBB0_1137
	s_andn2_b64 vcc, exec, s[14:15]
	s_cbranch_vccnz .LBB0_1136
	s_barrier
	s_branch .LBB0_1136
